# GEMM prologue issues K-tile 1 stage loads before the first wait; fast next-unit coordinate path; up-epilogue relu without separate NaN-canonicalize; attention bias prefetch multiply deferred past PV (
# speedup vs baseline: 1.0212x; 1.0050x over previous
; #define GAS __attribute__((address_space(1)))
; #define LAS __attribute__((address_space(3)))
; __device__ __forceinline__ void attn_phase(LAS unsigned char* lds, bf16* Qb, const bf16* Kb, const bf16* Vb, const float* rpb_l, int seq_len, int G, int bx, int tid, int wave, int lane) {
;     ...
;     for (int loc = lc; loc < per; loc += nx) {
;         const int h = 2 * hp + hh;
;         const size_t qoff = (size_t)(tb + r * 64 + qc) * D + h * 64;
;         const bf16* kbase = Kb + ((size_t)(h * 8 + fq) * CH + (tb + r0 * 64 + fr)) * 8;
;         const int drb = r0 - r + 7;
;         __syncthreads();
;         {
;             const int a = wave >> 1, ub = (wave & 1) * 2;
; #pragma unroll
;             for (int i = 0; i < 16; ++i) { const int kr = 2 * (ub + (i >> 3)) + (i & 1), cb = 16 * a + 4 * ((i & 7) >> 1);
;                 const bf16* src = Vb + (size_t)(tb + (r0 + kr) * 64 + cb) * D + hp * 128 + voff[i & 3];
;                 __builtin_amdgcn_global_load_lds((const unsigned*)src, (LAS unsigned*)(lds + (wave * 16 + i) * 1024), 16, 0, 0); }
;         }
;         f32x4 S[8];
;         float mx = -3.0e38f;
;         const LAS float* bptr[4];
; #pragma unroll
;         for (int i = 0; i < 4; ++i) { const int kc = 16 * (sel[i] ? a0 : a1) + 4 * fq + i; bptr[i] = bias + hh * 465 + drb * 31 + min(max(kc - qc + 15, 0), 30); }
; #pragma unroll
;         for (int kr = 0; kr < 8; ++kr) {
;             f32x4 z0 = {0.f, 0.f, 0.f, 0.f}, z1 = {0.f, 0.f, 0.f, 0.f};
;             z0 = __builtin_amdgcn_mfma_f32_16x16x32_bf16(kf[kr & 3][0][0], qf0, z0, 0, 0, 0);
;             z0 = __builtin_amdgcn_mfma_f32_16x16x32_bf16(kf[kr & 3][0][1], qf1, z0, 0, 0, 0);
;             z1 = __builtin_amdgcn_mfma_f32_16x16x32_bf16(kf[kr & 3][1][0], qf0, z1, 0, 0, 0);
;             z1 = __builtin_amdgcn_mfma_f32_16x16x32_bf16(kf[kr & 3][1][1], qf1, z1, 0, 0, 0);
;             f32x4 z;
; #pragma unroll
;             for (int i = 0; i < 4; ++i) { z[i] = (sel[i] ? z0[i] : z1[i]) + bptr[i][kr * 31]; mx = fmaxf(mx, z[i]); }
;             S[kr] = z;
;             if (kr < 4) {
; #pragma unroll
;                 for (int ai = 0; ai < 2; ++ai) { const bf16* kp = kbase + ((kr + 4) * 64 + 16 * (ai ? a1 : a0)) * 8; kf[kr & 3][ai][0] = *(const GAS bf16x8*)kp; kf[kr & 3][ai][1] = *(const GAS bf16x8*)(kp + (size_t)4 * CH * 8); }
;             }
;         }
.LBB0_96:
	s_lshl_b32 s15, s23, 6
	s_lshl_b32 s64, s21, 1
	s_add_i32 s4, s15, s63
	s_add_i32 s64, s64, s3
	v_add_u32_e32 v74, s4, v98
	s_add_i32 s14, s63, s28
	s_lshl_b32 s4, s21, 8
	s_add_u32 s6, s26, s4
	s_addc_u32 s7, s27, 0
	s_add_i32 s68, s15, s30
	s_add_i32 s4, s68, s14
	s_ashr_i32 s5, s4, 31
	s_lshl_b64 s[4:5], s[4:5], 11
	s_add_u32 s12, s6, s4
	s_addc_u32 s13, s7, s5
	s_mov_b32 m0, s34
	s_waitcnt lgkmcnt(0)
	s_barrier
	global_load_lds_dwordx4 v123, s[12:13]
	s_add_i32 s12, s15, 64
	s_add_i32 s13, s12, s30
	s_add_i32 s4, s13, s14
	s_ashr_i32 s5, s4, 31
	s_lshl_b64 s[4:5], s[4:5], 11
	s_add_u32 s4, s6, s4
	s_addc_u32 s5, s7, s5
	s_mov_b32 m0, s35
	s_add_i32 s69, s14, 4
	global_load_lds_dwordx4 v124, s[4:5]
	s_add_i32 s4, s68, s69
	s_ashr_i32 s5, s4, 31
	s_lshl_b64 s[4:5], s[4:5], 11
	s_add_u32 s4, s6, s4
	s_addc_u32 s5, s7, s5
	s_add_i32 m0, s34, 0x800
	v_mfma_f32_16x16x32_bf16 v[40:43], v[40:43], v[0:3], 0
	global_load_lds_dwordx4 v125, s[4:5]
	s_add_i32 s4, s13, s69
	s_ashr_i32 s5, s4, 31
	s_lshl_b64 s[4:5], s[4:5], 11
	s_add_u32 s4, s6, s4
	s_addc_u32 s5, s7, s5
	s_mov_b32 m0, s37
	s_add_i32 s70, s14, 8
	global_load_lds_dwordx4 v126, s[4:5]
	s_add_i32 s4, s68, s70
	s_ashr_i32 s5, s4, 31
	s_lshl_b64 s[4:5], s[4:5], 11
	s_add_u32 s4, s6, s4
	s_addc_u32 s5, s7, s5
	s_add_i32 m0, s34, 0x1000
	v_mfma_f32_16x16x32_bf16 v[32:35], v[32:35], v[0:3], 0
	global_load_lds_dwordx4 v123, s[4:5]
	s_add_i32 s4, s13, s70
	s_ashr_i32 s5, s4, 31
	s_lshl_b64 s[4:5], s[4:5], 11
	s_add_u32 s4, s6, s4
	s_addc_u32 s5, s7, s5
	s_mov_b32 m0, s48
	s_add_i32 s71, s14, 12
	global_load_lds_dwordx4 v124, s[4:5]
	s_add_i32 s4, s68, s71
	s_ashr_i32 s5, s4, 31
	s_lshl_b64 s[4:5], s[4:5], 11
	s_add_u32 s4, s6, s4
	s_addc_u32 s5, s7, s5
	s_mov_b32 m0, s49
	v_mfma_f32_16x16x32_bf16 v[40:43], v[44:47], v[4:7], v[40:43]
	global_load_lds_dwordx4 v125, s[4:5]
	s_add_i32 s4, s13, s71
	s_ashr_i32 s5, s4, 31
	s_lshl_b64 s[4:5], s[4:5], 11
	s_add_u32 s4, s6, s4
	s_addc_u32 s5, s7, s5
	s_mov_b32 m0, s50
	s_add_i32 s13, s15, s31
	global_load_lds_dwordx4 v126, s[4:5]
	s_add_i32 s4, s13, s14
	s_ashr_i32 s5, s4, 31
	s_lshl_b64 s[4:5], s[4:5], 11
	s_add_u32 s4, s6, s4
	s_addc_u32 s5, s7, s5
	s_add_i32 m0, s34, 0x2000
	s_add_i32 s12, s12, s31
	global_load_lds_dwordx4 v123, s[4:5]
	s_add_i32 s4, s12, s14
	s_ashr_i32 s5, s4, 31
	s_lshl_b64 s[4:5], s[4:5], 11
	s_add_u32 s4, s6, s4
	s_addc_u32 s5, s7, s5
	s_mov_b32 m0, s51
	v_mfma_f32_16x16x32_bf16 v[28:31], v[28:31], v[4:7], v[32:35]
	global_load_lds_dwordx4 v124, s[4:5]
	s_add_i32 s4, s13, s69
	s_ashr_i32 s5, s4, 31
	s_lshl_b64 s[4:5], s[4:5], 11
	s_add_u32 s4, s6, s4
	s_addc_u32 s5, s7, s5
	s_mov_b32 m0, s52
	v_lshl_or_b32 v72, s64, 3, v100
	global_load_lds_dwordx4 v125, s[4:5]
	s_add_i32 s4, s12, s69
	s_ashr_i32 s5, s4, 31
	s_lshl_b64 s[4:5], s[4:5], 11
	s_add_u32 s4, s6, s4
	s_addc_u32 s5, s7, s5
	s_mov_b32 m0, s56
	v_ashrrev_i32_e32 v73, 31, v72
	global_load_lds_dwordx4 v126, s[4:5]
	s_add_i32 s4, s13, s70
	s_ashr_i32 s5, s4, 31
	s_lshl_b64 s[4:5], s[4:5], 11
	s_add_u32 s4, s6, s4
	s_addc_u32 s5, s7, s5
	s_add_i32 m0, s34, 0x3000
	v_cndmask_b32_e64 v28, v28, v40, s[40:41]
	global_load_lds_dwordx4 v123, s[4:5]
	s_add_i32 s4, s12, s70
	s_ashr_i32 s5, s4, 31
	s_lshl_b64 s[4:5], s[4:5], 11
	s_add_u32 s4, s6, s4
	s_addc_u32 s5, s7, s5
	s_mov_b32 m0, s57
	v_lshlrev_b64 v[72:73], 19, v[72:73]
	global_load_lds_dwordx4 v124, s[4:5]
	s_add_i32 s4, s13, s71
	s_ashr_i32 s5, s4, 31
	s_lshl_b64 s[4:5], s[4:5], 11
	s_add_u32 s4, s6, s4
	s_addc_u32 s5, s7, s5
	s_mov_b32 m0, s58
	v_ashrrev_i32_e32 v75, 31, v74
	global_load_lds_dwordx4 v125, s[4:5]
	s_add_i32 s4, s12, s71
	s_ashr_i32 s5, s4, 31
	s_lshl_b64 s[4:5], s[4:5], 11
	s_add_u32 s4, s6, s4
	s_addc_u32 s5, s7, s5
	s_mov_b32 m0, s59
	v_lshl_add_u64 v[72:73], s[10:11], 0, v[72:73]
	global_load_lds_dwordx4 v126, s[4:5]
	s_sub_i32 s4, s23, s62
	s_mulk_i32 s4, 0x7c
	s_add_i32 s4, s29, s4
	v_lshl_add_u32 v94, v106, 2, s4
	v_lshl_add_u32 v95, v107, 2, s4
	v_lshl_add_u32 v97, v109, 2, s4
	ds_read2_b32 v[84:85], v94 offset0:217 offset1:248
	v_lshl_add_u32 v127, v110, 2, s4
	ds_read2_b32 v[88:89], v95 offset0:217 offset1:248
	ds_read2_b32 v[90:91], v97 offset0:217 offset1:248
	ds_read2_b32 v[92:93], v127 offset0:217 offset1:248
	s_waitcnt lgkmcnt(0)
	v_add_f32_e32 v83, v84, v28
	v_cndmask_b32_e64 v28, v29, v41, s[42:43]
	v_cndmask_b32_e64 v29, v30, v42, s[44:45]
	v_add_f32_e32 v82, v28, v88
	s_mov_b32 s4, 0xff61b1e6
	v_add_f32_e32 v81, v29, v90
	v_cndmask_b32_e64 v29, v31, v43, s[46:47]
	v_lshl_add_u64 v[72:73], v[74:75], 4, v[72:73]
	v_max3_f32 v28, v83, s4, v82
	v_add_f32_e32 v80, v29, v92
	s_lshl_b32 s78, s24, 1
	v_max3_f32 v84, v28, v81, v80
	v_lshl_add_u64 v[28:29], v[72:73], 0, s[78:79]
	v_add_co_u32_e32 v78, vcc, s77, v28
	s_lshl_b32 s14, s25, 1
	s_nop 0
	v_addc_co_u32_e32 v79, vcc, 0, v29, vcc
	v_add_co_u32_e32 v76, vcc, s87, v28
	s_mov_b32 s15, s79
	s_nop 0
	v_addc_co_u32_e32 v77, vcc, 0, v29, vcc
	v_lshl_add_u64 v[28:29], v[72:73], 0, s[14:15]
	v_add_co_u32_e32 v74, vcc, s77, v28
	global_load_dwordx4 v[40:43], v[78:79], off
	global_load_dwordx4 v[44:47], v[76:77], off
	v_addc_co_u32_e32 v75, vcc, 0, v29, vcc
	global_load_dwordx4 v[32:35], v[74:75], off
	v_mfma_f32_16x16x32_bf16 v[8:11], v[8:11], v[0:3], 0
	v_add_co_u32_e32 v72, vcc, s87, v28
	v_add_u32_e32 v128, 0x400, v94
	s_nop 0
	v_addc_co_u32_e32 v73, vcc, 0, v29, vcc
	global_load_dwordx4 v[28:31], v[72:73], off
	v_mfma_f32_16x16x32_bf16 v[8:11], v[12:15], v[4:7], v[8:11]
	v_add_u32_e32 v96, 0x400, v95
	v_add_u32_e32 v97, 0x400, v97
	v_add_u32_e32 v127, 0x400, v127
	v_mfma_f32_16x16x32_bf16 v[12:15], v[20:23], v[0:3], 0
	s_cmp_lt_i32 s33, s0
	s_cselect_b64 s[12:13], -1, 0
	s_cmp_ge_i32 s33, s0
	v_mfma_f32_16x16x32_bf16 v[12:15], v[36:39], v[4:7], v[12:15]
	v_mfma_f32_16x16x32_bf16 v[48:51], v[48:51], v[0:3], 0
	v_mfma_f32_16x16x32_bf16 v[48:51], v[60:63], v[4:7], v[48:51]
	s_nop 5
	v_cndmask_b32_e64 v8, v12, v8, s[40:41]
	v_add_f32_e32 v87, v85, v8
	v_cndmask_b32_e64 v8, v13, v9, s[42:43]
	v_cndmask_b32_e64 v9, v14, v10, s[44:45]
	v_add_f32_e32 v86, v8, v89
	v_add_f32_e32 v85, v9, v91
	v_cndmask_b32_e64 v9, v15, v11, s[46:47]
	v_max3_f32 v8, v84, v87, v86
	v_add_f32_e32 v84, v9, v93
	v_max3_f32 v88, v8, v85, v84
	global_load_dwordx4 v[8:11], v[78:79], off offset:1024
	global_load_dwordx4 v[12:15], v[76:77], off offset:1024
	global_load_dwordx4 v[20:23], v[74:75], off offset:1024
	global_load_dwordx4 v[36:39], v[72:73], off offset:1024
	v_mfma_f32_16x16x32_bf16 v[60:63], v[64:67], v[0:3], 0
	ds_read2_b32 v[92:93], v128 offset0:23 offset1:54
	ds_read2_b32 v[130:131], v96 offset0:23 offset1:54
	ds_read2_b32 v[132:133], v97 offset0:23 offset1:54
	v_mfma_f32_16x16x32_bf16 v[60:63], v[68:71], v[4:7], v[60:63]
	ds_read2_b32 v[134:135], v127 offset0:23 offset1:54
	v_mfma_f32_16x16x32_bf16 v[16:19], v[16:19], v[0:3], 0
	v_mfma_f32_16x16x32_bf16 v[16:19], v[24:27], v[4:7], v[16:19]
	s_nop 4
	v_cndmask_b32_e64 v48, v60, v48, s[40:41]
	s_waitcnt lgkmcnt(0)
; #define GAS __attribute__((address_space(1)))
; __device__ __forceinline__ void attn_phase(LAS unsigned char* lds, bf16* Qb, const bf16* Kb, const bf16* Vb, const float* rpb_l, int seq_len, int G, int bx, int tid, int wave, int lane) {
;     ...
;         for (int kr = 0; kr < 8; ++kr) {
;             f32x4 z0 = {0.f, 0.f, 0.f, 0.f}, z1 = {0.f, 0.f, 0.f, 0.f};
;             z0 = __builtin_amdgcn_mfma_f32_16x16x32_bf16(kf[kr & 3][0][0], qf0, z0, 0, 0, 0);
;             z0 = __builtin_amdgcn_mfma_f32_16x16x32_bf16(kf[kr & 3][0][1], qf1, z0, 0, 0, 0);
;             z1 = __builtin_amdgcn_mfma_f32_16x16x32_bf16(kf[kr & 3][1][0], qf0, z1, 0, 0, 0);
;             z1 = __builtin_amdgcn_mfma_f32_16x16x32_bf16(kf[kr & 3][1][1], qf1, z1, 0, 0, 0);
;             f32x4 z;
; #pragma unroll
;             for (int i = 0; i < 4; ++i) { z[i] = (sel[i] ? z0[i] : z1[i]) + bptr[i][kr * 31]; mx = fmaxf(mx, z[i]); }
;             S[kr] = z;
;             if (kr < 4) {
; #pragma unroll
;                 for (int ai = 0; ai < 2; ++ai) { const bf16* kp = kbase + ((kr + 4) * 64 + 16 * (ai ? a1 : a0)) * 8; kf[kr & 3][ai][0] = *(const GAS bf16x8*)kp; kf[kr & 3][ai][1] = *(const GAS bf16x8*)(kp + (size_t)4 * CH * 8); }
;             }
;         }
	v_add_f32_e32 v91, v92, v48
	v_cndmask_b32_e64 v48, v61, v49, s[42:43]
	v_cndmask_b32_e64 v49, v62, v50, s[44:45]
	v_add_f32_e32 v90, v48, v130
	v_add_f32_e32 v89, v49, v132
	v_cndmask_b32_e64 v49, v63, v51, s[46:47]
	v_max3_f32 v48, v88, v91, v90
	v_add_f32_e32 v88, v49, v134
	v_max3_f32 v92, v48, v89, v88
	global_load_dwordx4 v[48:51], v[78:79], off offset:2048
	global_load_dwordx4 v[60:63], v[76:77], off offset:2048
	global_load_dwordx4 v[64:67], v[74:75], off offset:2048
	global_load_dwordx4 v[68:71], v[72:73], off offset:2048
	v_mfma_f32_16x16x32_bf16 v[24:27], v[52:55], v[0:3], 0
	v_mfma_f32_16x16x32_bf16 v[24:27], v[56:59], v[4:7], v[24:27]
	s_nop 7
	v_cndmask_b32_e64 v16, v24, v16, s[40:41]
	v_add_f32_e32 v95, v93, v16
	v_cndmask_b32_e64 v16, v25, v17, s[42:43]
	v_cndmask_b32_e64 v17, v26, v18, s[44:45]
	v_add_f32_e32 v94, v16, v131
	v_add_f32_e32 v93, v17, v133
	v_cndmask_b32_e64 v17, v27, v19, s[46:47]
	v_max3_f32 v16, v92, v95, v94
	v_add_f32_e32 v92, v17, v135
	v_max3_f32 v129, v16, v93, v92
	global_load_dwordx4 v[16:19], v[78:79], off offset:3072
	global_load_dwordx4 v[24:27], v[76:77], off offset:3072
	global_load_dwordx4 v[52:55], v[74:75], off offset:3072
	global_load_dwordx4 v[56:59], v[72:73], off offset:3072
	s_waitcnt vmcnt(0)
	v_mfma_f32_16x16x32_bf16 v[72:75], v[40:43], v[0:3], 0
	ds_read2_b32 v[130:131], v128 offset0:85 offset1:116
	ds_read2_b32 v[132:133], v96 offset0:85 offset1:116
	ds_read2_b32 v[134:135], v97 offset0:85 offset1:116
	v_mfma_f32_16x16x32_bf16 v[76:79], v[32:35], v[0:3], 0
	ds_read2_b32 v[136:137], v127 offset0:85 offset1:116
	v_mfma_f32_16x16x32_bf16 v[72:75], v[44:47], v[4:7], v[72:75]
	v_mfma_f32_16x16x32_bf16 v[76:79], v[28:31], v[4:7], v[76:79]
	s_nop 7
	v_cndmask_b32_e64 v72, v76, v72, s[40:41]
	s_waitcnt lgkmcnt(3)
	v_add_f32_e32 v141, v130, v72
	v_cndmask_b32_e64 v72, v77, v73, s[42:43]
	s_waitcnt lgkmcnt(2)
	v_add_f32_e32 v142, v72, v132
	v_cndmask_b32_e64 v72, v78, v74, s[44:45]
	s_waitcnt lgkmcnt(1)
	v_add_f32_e32 v143, v72, v134
	v_cndmask_b32_e64 v72, v79, v75, s[46:47]
	s_waitcnt lgkmcnt(0)
	v_add_f32_e32 v136, v72, v136
	v_mfma_f32_16x16x32_bf16 v[72:75], v[8:11], v[0:3], 0
	v_mfma_f32_16x16x32_bf16 v[76:79], v[20:23], v[0:3], 0
	v_mfma_f32_16x16x32_bf16 v[72:75], v[12:15], v[4:7], v[72:75]
	v_mfma_f32_16x16x32_bf16 v[76:79], v[36:39], v[4:7], v[76:79]
	s_nop 7
	v_cndmask_b32_e64 v72, v76, v72, s[40:41]
	v_add_f32_e32 v144, v131, v72
	v_cndmask_b32_e64 v72, v77, v73, s[42:43]
	v_add_f32_e32 v145, v72, v133
	v_cndmask_b32_e64 v72, v78, v74, s[44:45]
	v_add_f32_e32 v146, v72, v135
	v_cndmask_b32_e64 v72, v79, v75, s[46:47]
	v_add_f32_e32 v137, v72, v137
	v_mfma_f32_16x16x32_bf16 v[72:75], v[48:51], v[0:3], 0
	ds_read2_b32 v[130:131], v128 offset0:147 offset1:178
	ds_read2_b32 v[132:133], v96 offset0:147 offset1:178
	ds_read2_b32 v[96:97], v97 offset0:147 offset1:178
	v_mfma_f32_16x16x32_bf16 v[76:79], v[64:67], v[0:3], 0
	ds_read2_b32 v[134:135], v127 offset0:147 offset1:178
	s_waitcnt vmcnt(0)
	s_waitcnt lgkmcnt(0)
	v_mfma_f32_16x16x32_bf16 v[72:75], v[60:63], v[4:7], v[72:75]
	s_barrier
; __device__ __forceinline__ unsigned cvtpk(float lo, float hi) { return pk2(lo, hi); }
; __device__ __forceinline__ void attn_phase(LAS unsigned char* lds, bf16* Qb, const bf16* Kb, const bf16* Vb, const float* rpb_l, int seq_len, int G, int bx, int tid, int wave, int lane) {
;     ...
;         mx = fmaxf(mx, __shfl_xor(mx, 16)); mx = fmaxf(mx, __shfl_xor(mx, 32));
;         float sum = 0.f;
; #pragma unroll
;         for (int kr = 0; kr < 8; ++kr)
; #pragma unroll
;             for (int i = 0; i < 4; ++i) { const float p = __builtin_amdgcn_exp2f(S[kr][i] - mx); S[kr][i] = p; sum += p; }
;         sum += __shfl_xor(sum, 16); sum += __shfl_xor(sum, 32);
;         bf16x8 pf[4][2];
; #pragma unroll
;         for (int u = 0; u < 4; ++u)
; #pragma unroll
;             for (int ai = 0; ai < 2; ++ai) {
;                 float pa[2][4];
; #pragma unroll
;                 for (int t = 0; t < 2; ++t)
; #pragma unroll
;                     for (int i = 0; i < 4; ++i) pa[t][i] = (sel[i] == (ai == 0)) ? S[2 * u + t][i] : 0.f;
;                 v4u pw; pw.x = cvtpk(pa[0][0], pa[0][1]); pw.y = cvtpk(pa[0][2], pa[0][3]); pw.z = cvtpk(pa[1][0], pa[1][1]); pw.w = cvtpk(pa[1][2], pa[1][3]);
;                 pf[u][ai] = __builtin_bit_cast(bf16x8, pw); }
;         asm volatile("s_waitcnt vmcnt(0)" ::: "memory");
;         __syncthreads();
;         const int nloc = loc + nx; const bool has_next = nloc < per;
;         const int r_cur = r, tb_cur = tb;
;         if (has_next) { id = xc * per + nloc; r = id & (rows - 1); hp = (id >> rows_shift) & 7; tb = (id >> (rows_shift + 3)) * seq_len; r0 = min(max(r - 4, 0), rows - 8); ATT_PREFETCH(); }
	v_mfma_f32_16x16x32_bf16 v[76:79], v[68:71], v[4:7], v[76:79]
	s_nop 7
	v_cndmask_b32_e64 v72, v76, v72, s[40:41]
	v_add_f32_e32 v147, v130, v72
	v_cndmask_b32_e64 v72, v77, v73, s[42:43]
	v_add_f32_e32 v148, v72, v132
	v_cndmask_b32_e64 v72, v78, v74, s[44:45]
	v_add_f32_e32 v149, v72, v96
	v_cndmask_b32_e64 v72, v79, v75, s[46:47]
	v_add_f32_e32 v127, v72, v134
	v_mfma_f32_16x16x32_bf16 v[72:75], v[16:19], v[0:3], 0
	v_max3_f32 v96, v129, v141, v142
	v_max3_f32 v96, v96, v143, v136
	v_max3_f32 v96, v96, v144, v145
	v_mfma_f32_16x16x32_bf16 v[76:79], v[52:55], v[0:3], 0
	v_max3_f32 v96, v96, v146, v137
	v_max3_f32 v96, v96, v147, v148
	v_max3_f32 v96, v96, v149, v127
	v_mfma_f32_16x16x32_bf16 v[72:75], v[24:27], v[4:7], v[72:75]
	v_mfma_f32_16x16x32_bf16 v[76:79], v[56:59], v[4:7], v[76:79]
	s_nop 7
	v_cndmask_b32_e64 v72, v76, v72, s[40:41]
	v_cndmask_b32_e64 v73, v77, v73, s[42:43]
	v_cndmask_b32_e64 v74, v78, v74, s[44:45]
	v_add_f32_e32 v72, v131, v72
	v_add_f32_e32 v73, v73, v133
	v_add_f32_e32 v97, v74, v97
	v_cndmask_b32_e64 v74, v79, v75, s[46:47]
	v_max3_f32 v76, v96, v72, v73
	v_add_f32_e32 v150, v74, v135
	v_max3_f32 v74, v76, v97, v150
	ds_bpermute_b32 v75, v103, v74
	s_waitcnt lgkmcnt(0)
	v_max_f32_e32 v75, v75, v75
	v_max_f32_e32 v74, v74, v75
	ds_bpermute_b32 v75, v104, v74
	s_waitcnt lgkmcnt(0)
	v_max_f32_e32 v75, v75, v75
	v_max_f32_e32 v151, v74, v75
	v_sub_f32_e32 v74, v83, v151
	v_exp_f32_e32 v74, v74
	v_sub_f32_e32 v75, v82, v151
	v_exp_f32_e32 v75, v75
	v_sub_f32_e32 v77, v81, v151
	v_exp_f32_e32 v129, v77
	v_sub_f32_e32 v77, v80, v151
	v_exp_f32_e32 v130, v77
	v_sub_f32_e32 v77, v87, v151
	v_add_f32_e32 v76, 0, v74
	v_exp_f32_e32 v132, v77
	v_sub_f32_e32 v77, v86, v151
	v_add_f32_e32 v76, v75, v76
	v_exp_f32_e32 v133, v77
	v_sub_f32_e32 v77, v85, v151
	v_add_f32_e32 v76, v129, v76
	v_exp_f32_e32 v134, v77
	v_sub_f32_e32 v77, v84, v151
	v_add_f32_e32 v76, v130, v76
	v_exp_f32_e32 v135, v77
	v_sub_f32_e32 v77, v91, v151
	v_add_f32_e32 v76, v132, v76
	v_exp_f32_e32 v96, v77
	v_sub_f32_e32 v77, v90, v151
	v_add_f32_e32 v76, v133, v76
	v_exp_f32_e32 v128, v77
	v_sub_f32_e32 v77, v89, v151
	v_add_f32_e32 v76, v134, v76
	v_exp_f32_e32 v138, v77
	v_sub_f32_e32 v77, v88, v151
	v_add_f32_e32 v76, v135, v76
	v_exp_f32_e32 v139, v77
	v_sub_f32_e32 v77, v95, v151
	v_add_f32_e32 v76, v96, v76
	v_exp_f32_e32 v140, v77
	v_sub_f32_e32 v77, v94, v151
	v_add_f32_e32 v76, v128, v76
	v_exp_f32_e32 v84, v77
	v_sub_f32_e32 v77, v93, v151
	v_add_f32_e32 v76, v138, v76
	v_exp_f32_e32 v85, v77
	v_sub_f32_e32 v77, v92, v151
	v_add_f32_e32 v76, v139, v76
	v_exp_f32_e32 v131, v77
	v_sub_f32_e32 v77, v141, v151
	v_add_f32_e32 v76, v140, v76
	v_exp_f32_e32 v83, v77
	v_add_f32_e32 v76, v84, v76
	v_add_f32_e32 v76, v85, v76
	v_add_f32_e32 v76, v131, v76
	v_add_f32_e32 v77, v83, v76
	v_sub_f32_e32 v76, v142, v151
	v_exp_f32_e32 v76, v76
	v_sub_f32_e32 v87, v147, v151
	v_exp_f32_e32 v92, v87
	v_sub_f32_e32 v87, v148, v151
	v_add_f32_e32 v78, v76, v77
	v_sub_f32_e32 v77, v143, v151
	v_exp_f32_e32 v77, v77
	v_exp_f32_e32 v93, v87
	v_sub_f32_e32 v87, v149, v151
	v_exp_f32_e32 v89, v87
	v_add_f32_e32 v79, v77, v78
	v_sub_f32_e32 v78, v136, v151
	v_exp_f32_e32 v78, v78
	v_sub_f32_e32 v87, v127, v151
	v_exp_f32_e32 v90, v87
	v_sub_f32_e32 v72, v72, v151
	v_add_f32_e32 v80, v78, v79
	v_sub_f32_e32 v79, v144, v151
	v_exp_f32_e32 v79, v79
	v_exp_f32_e32 v91, v72
	v_sub_f32_e32 v73, v73, v151
	v_add_f32_e32 v81, v79, v80
	v_sub_f32_e32 v80, v145, v151
	v_exp_f32_e32 v80, v80
	s_nop 0
	v_add_f32_e32 v82, v80, v81
	v_sub_f32_e32 v81, v146, v151
	v_exp_f32_e32 v81, v81
	s_nop 0
	v_add_f32_e32 v86, v81, v82
	v_sub_f32_e32 v82, v137, v151
	v_exp_f32_e32 v82, v82
	s_nop 0
	v_add_f32_e32 v86, v82, v86
	v_add_f32_e32 v86, v92, v86
	v_add_f32_e32 v86, v93, v86
	v_add_f32_e32 v86, v89, v86
	v_add_f32_e32 v86, v90, v86
	v_add_f32_e32 v72, v91, v86
	v_exp_f32_e32 v86, v73
	v_sub_f32_e32 v73, v97, v151
	v_exp_f32_e32 v87, v73
	v_sub_f32_e32 v73, v150, v151
	v_exp_f32_e32 v88, v73
	v_add_f32_e32 v72, v86, v72
	v_add_f32_e32 v72, v87, v72
	v_add_f32_e32 v72, v88, v72
	ds_bpermute_b32 v73, v103, v72
	s_waitcnt lgkmcnt(0)
	v_add_f32_e32 v97, v72, v73
	ds_bpermute_b32 v127, v104, v97
	s_cbranch_scc1 .LBB0_100
	s_add_i32 s4, s17, s33
	s_and_b32 s60, s4, s18
	s_ashr_i32 s5, s4, s16
	s_ashr_i32 s4, s4, s19
	s_lshl_b32 s61, s4, s20
	s_max_i32 s4, s60, 4
	s_and_b32 s21, s5, 7
	s_add_i32 s4, s4, -4
	s_min_i32 s23, s4, s22
	s_lshl_b32 s4, s21, 1
	s_add_i32 s6, s4, s3
	v_lshl_or_b32 v8, s6, 3, v100
	v_ashrrev_i32_e32 v9, 31, v8
	v_or_b32_e32 v10, s61, v98
	s_lshl_b32 s4, s60, 6
	v_lshl_add_u32 v10, s23, 6, v10
	v_lshlrev_b64 v[8:9], 19, v[8:9]
	s_add_i32 s4, s61, s4
	v_ashrrev_i32_e32 v11, 31, v10
	v_lshl_add_u64 v[8:9], s[10:11], 0, v[8:9]
	v_add_u32_e32 v0, s4, v99
	v_lshl_add_u64 v[8:9], v[10:11], 4, v[8:9]
	v_ashrrev_i32_e32 v1, 31, v0
	v_lshl_add_u64 v[16:17], v[8:9], 0, s[78:79]
	s_lshl_b32 s4, s6, 6
	v_lshlrev_b64 v[0:1], 11, v[0:1]
	v_add_co_u32_e32 v24, vcc, s86, v16
	s_ashr_i32 s5, s4, 31
	v_lshl_add_u64 v[0:1], s[8:9], 0, v[0:1]
	v_addc_co_u32_e32 v25, vcc, 0, v17, vcc
	v_lshl_add_u64 v[52:53], v[8:9], 0, s[14:15]
	v_lshl_add_u64 v[0:1], s[4:5], 1, v[0:1]
	v_lshlrev_b32_e32 v2, 1, v102
	v_mov_b32_e32 v3, v209
	v_add_co_u32_e32 v56, vcc, s86, v52
	v_lshl_add_u64 v[4:5], v[0:1], 0, v[2:3]
	s_nop 0
	v_addc_co_u32_e32 v57, vcc, 0, v53, vcc
	global_load_dwordx4 v[0:3], v[4:5], off
	s_nop 0
	global_load_dwordx4 v[4:7], v[4:5], off offset:64
	s_nop 0
	global_load_dwordx4 v[40:43], v[16:17], off
	global_load_dwordx4 v[8:11], v[16:17], off offset:1024
	global_load_dwordx4 v[44:47], v[24:25], off
	global_load_dwordx4 v[12:15], v[24:25], off offset:1024
	global_load_dwordx4 v[32:35], v[52:53], off
	global_load_dwordx4 v[20:23], v[52:53], off offset:1024
	global_load_dwordx4 v[28:31], v[56:57], off
	global_load_dwordx4 v[36:39], v[56:57], off offset:1024
	global_load_dwordx4 v[48:51], v[16:17], off offset:2048
	s_nop 0
	global_load_dwordx4 v[16:19], v[16:17], off offset:3072
	s_nop 0
	global_load_dwordx4 v[60:63], v[24:25], off offset:2048
	s_nop 0
	global_load_dwordx4 v[24:27], v[24:25], off offset:3072
	s_nop 0
	global_load_dwordx4 v[64:67], v[52:53], off offset:2048
	s_nop 0
	global_load_dwordx4 v[52:55], v[52:53], off offset:3072
	s_nop 0
	global_load_dwordx4 v[68:71], v[56:57], off offset:2048
	s_nop 0
	global_load_dwordx4 v[56:59], v[56:57], off offset:3072
	s_mul_i32 s4, s21, 0x3a2
	v_add_u32_e32 v72, s4, v188
	v_readlane_b32 s4, v255, 0
	v_ashrrev_i32_e32 v73, 31, v72
	v_readlane_b32 s5, v255, 1
	v_mov_b32_e32 v105, 0
	s_nop 0
	v_lshl_add_u64 v[72:73], v[72:73], 2, s[4:5]
	global_load_dword v175, v[72:73], off
	s_and_saveexec_b64 s[14:15], s[38:39]
	s_cbranch_execz .LBB0_99
	global_load_dword v176, v[72:73], off offset:2048

; #define LAS __attribute__((address_space(3)))
; __device__ __forceinline__ s16x4 vtr(const LAS unsigned char* p) { return __builtin_bit_cast(s16x4, __builtin_amdgcn_ds_read_tr16_b64_v4i16((LAS s16x4*)p)); }
; __device__ __forceinline__ void attn_phase(LAS unsigned char* lds, bf16* Qb, const bf16* Kb, const bf16* Vb, const float* rpb_l, int seq_len, int G, int bx, int tid, int wave, int lane) {
;     ...
;         f32x4 O[4];
; #pragma unroll
;         for (int c = 0; c < 4; ++c) O[c] = (f32x4){0.f, 0.f, 0.f, 0.f};
;         const LAS unsigned char* vb[2][2][4];
; #pragma unroll
;         for (int ai = 0; ai < 2; ++ai)
; #pragma unroll
;             for (int t = 0; t < 2; ++t)
; #pragma unroll
;                 for (int c = 0; c < 4; ++c) { const int rho = 8 * fq + 4 * t + q4, chn = 2 * (4 * hh + c) + (p4 >> 1);
;                     vb[ai][t][c] = lds + (ai ? a1 : a0) * 32768 + 256 * rho + 16 * (chn ^ (((rho & 3) << 2) | ((rho >> 2) & 3))) + 8 * (p4 & 1); }
; #pragma unroll
;         for (int u = 0; u < 4; ++u) {
; #pragma unroll
;             for (int ai = 0; ai < 2; ++ai) {
; #pragma unroll
;                 for (int c = 0; c < 4; ++c) {
;                     const s16x4 v0 = vtr(vb[ai][0][c] + u * 8192), v1 = vtr(vb[ai][1][c] + u * 8192);
;                     const bf16x8 vf = __builtin_shufflevector(v0, v1, 0, 1, 2, 3, 4, 5, 6, 7);
;                     O[c] = __builtin_amdgcn_mfma_f32_16x16x32_bf16(vf, pf[u][ai], O[c], 0, 0, 0);
;                 }
;             }
;         }
.LBB0_100:
	v_cndmask_b32_e64 v72, 0, v74, s[40:41]
	v_cndmask_b32_e64 v73, 0, v75, s[42:43]
	v_cndmask_b32_e64 v94, 0, v129, s[44:45]
	v_cndmask_b32_e64 v95, 0, v130, s[46:47]
	v_add_u32_e32 v144, v112, v113
	v_add_u32_e32 v143, v117, v111
	v_cndmask_b32_e64 v136, 0, v132, s[40:41]
	v_cndmask_b32_e64 v137, 0, v133, s[42:43]
	v_cndmask_b32_e64 v141, 0, v134, s[44:45]
	v_cndmask_b32_e64 v142, 0, v135, s[46:47]
	v_cvt_pk_bf16_f32 v146, v72, v73
	v_cvt_pk_bf16_f32 v147, v94, v95
	v_cndmask_b32_e64 v72, v74, 0, s[40:41]
	v_cndmask_b32_e64 v73, v75, 0, s[42:43]
	v_cndmask_b32_e64 v74, v129, 0, s[44:45]
	v_cndmask_b32_e64 v75, v130, 0, s[46:47]
	v_cndmask_b32_e64 v94, v132, 0, s[40:41]
	v_cndmask_b32_e64 v95, v133, 0, s[42:43]
	v_cndmask_b32_e64 v129, v134, 0, s[44:45]
	v_cndmask_b32_e64 v130, v135, 0, s[46:47]
	ds_read_b64_tr_b16 v[132:133], v144
	ds_read_b64_tr_b16 v[134:135], v143
	v_cvt_pk_bf16_f32 v148, v136, v137
	v_cvt_pk_bf16_f32 v149, v141, v142
	v_add_u32_e32 v142, v112, v114
	ds_read_b64_tr_b16 v[150:151], v142
	v_add_u32_e32 v141, v117, v118
	s_waitcnt lgkmcnt(1)
	v_mfma_f32_16x16x32_bf16 v[154:157], v[132:135], v[146:149], 0
	v_add_u32_e32 v137, v112, v115
	v_add_u32_e32 v136, v117, v119
	v_add_u32_e32 v135, v112, v116
	v_add_u32_e32 v134, v117, v120
	ds_read_b64_tr_b16 v[152:153], v141
	ds_read_b64_tr_b16 v[158:159], v137
	ds_read_b64_tr_b16 v[160:161], v136
	ds_read_b64_tr_b16 v[166:167], v135
	ds_read_b64_tr_b16 v[168:169], v134
	v_cvt_pk_bf16_f32 v72, v72, v73
	v_cvt_pk_bf16_f32 v73, v74, v75
	v_cvt_pk_bf16_f32 v75, v129, v130
	v_cndmask_b32_e64 v129, 0, v138, s[44:45]
	v_cndmask_b32_e64 v130, 0, v139, s[46:47]
	v_cvt_pk_bf16_f32 v163, v129, v130
	v_add_u32_e32 v133, v121, v113
	v_add_u32_e32 v132, v122, v111
	v_add_u32_e32 v130, v121, v114
	v_add_u32_e32 v129, v122, v118
	s_waitcnt lgkmcnt(4)
	v_mfma_f32_16x16x32_bf16 v[150:153], v[150:153], v[146:149], 0
	ds_read_b64_tr_b16 v[170:171], v133
	ds_read_b64_tr_b16 v[172:173], v132
	v_cvt_pk_bf16_f32 v74, v94, v95
	s_waitcnt lgkmcnt(4)
	v_mfma_f32_16x16x32_bf16 v[158:161], v[158:161], v[146:149], 0
	v_cndmask_b32_e64 v94, 0, v96, s[40:41]
	v_cndmask_b32_e64 v95, 0, v128, s[42:43]
	v_cndmask_b32_e64 v145, 0, v140, s[40:41]
	s_waitcnt lgkmcnt(2)
	v_mfma_f32_16x16x32_bf16 v[146:149], v[166:169], v[146:149], 0
	ds_read_b64_tr_b16 v[166:167], v130
	ds_read_b64_tr_b16 v[168:169], v129
	v_cndmask_b32_e64 v164, 0, v84, s[42:43]
	v_cndmask_b32_e64 v165, 0, v85, s[44:45]
	v_cndmask_b32_e64 v174, 0, v131, s[46:47]
	v_cvt_pk_bf16_f32 v162, v94, v95
	v_cvt_pk_bf16_f32 v164, v145, v164
	v_cvt_pk_bf16_f32 v165, v165, v174
	v_cndmask_b32_e64 v145, v96, 0, s[40:41]
	v_cndmask_b32_e64 v174, v128, 0, s[42:43]
	v_add_u32_e32 v128, v121, v115
	v_add_u32_e32 v96, v122, v119
	v_add_u32_e32 v95, v121, v116
	v_add_u32_e32 v94, v122, v120
	s_waitcnt lgkmcnt(2)
	v_mfma_f32_16x16x32_bf16 v[154:157], v[170:173], v[72:75], v[154:157]
	ds_read_b64_tr_b16 v[170:171], v128
	ds_read_b64_tr_b16 v[172:173], v96
	v_cndmask_b32_e64 v138, v138, 0, s[44:45]
	s_waitcnt lgkmcnt(2)
	v_mfma_f32_16x16x32_bf16 v[150:153], v[166:169], v[72:75], v[150:153]
	ds_read_b64_tr_b16 v[166:167], v95
	ds_read_b64_tr_b16 v[168:169], v94
	v_cndmask_b32_e64 v139, v139, 0, s[46:47]
	s_waitcnt lgkmcnt(2)
	v_mfma_f32_16x16x32_bf16 v[158:161], v[170:173], v[72:75], v[158:161]
	ds_read_b64_tr_b16 v[170:171], v144 offset:8192
	ds_read_b64_tr_b16 v[172:173], v143 offset:8192
	v_cndmask_b32_e64 v140, v140, 0, s[40:41]
	v_cndmask_b32_e64 v84, v84, 0, s[42:43]
	s_waitcnt lgkmcnt(2)
	v_mfma_f32_16x16x32_bf16 v[72:75], v[166:169], v[72:75], v[146:149]
	s_nop 2
	ds_read_b64_tr_b16 v[146:147], v142 offset:8192
	ds_read_b64_tr_b16 v[148:149], v141 offset:8192
	v_cndmask_b32_e64 v85, v85, 0, s[44:45]
	v_cndmask_b32_e64 v131, v131, 0, s[46:47]
	s_waitcnt lgkmcnt(2)
	v_mfma_f32_16x16x32_bf16 v[154:157], v[170:173], v[162:165], v[154:157]
	ds_read_b64_tr_b16 v[170:171], v137 offset:8192
	ds_read_b64_tr_b16 v[172:173], v136 offset:8192
	v_cvt_pk_bf16_f32 v166, v145, v174
	v_cvt_pk_bf16_f32 v167, v138, v139
	s_waitcnt lgkmcnt(2)
	v_mfma_f32_16x16x32_bf16 v[146:149], v[146:149], v[162:165], v[150:153]
	s_nop 2
	ds_read_b64_tr_b16 v[150:151], v135 offset:8192
	ds_read_b64_tr_b16 v[152:153], v134 offset:8192
	v_cvt_pk_bf16_f32 v168, v140, v84
	v_cvt_pk_bf16_f32 v169, v85, v131
	s_waitcnt lgkmcnt(2)
	v_mfma_f32_16x16x32_bf16 v[158:161], v[170:173], v[162:165], v[158:161]
	ds_read_b64_tr_b16 v[170:171], v133 offset:8192
	ds_read_b64_tr_b16 v[172:173], v132 offset:8192
	v_cndmask_b32_e64 v84, 0, v83, s[40:41]
	v_cndmask_b32_e64 v85, 0, v76, s[42:43]
	s_waitcnt lgkmcnt(2)
	v_mfma_f32_16x16x32_bf16 v[72:75], v[150:153], v[162:165], v[72:75]
	ds_read_b64_tr_b16 v[150:151], v130 offset:8192
	ds_read_b64_tr_b16 v[152:153], v129 offset:8192
	ds_read_b64_tr_b16 v[162:163], v128 offset:8192
	ds_read_b64_tr_b16 v[164:165], v96 offset:8192
	v_cndmask_b32_e64 v131, 0, v77, s[44:45]
	s_waitcnt lgkmcnt(2)
	v_mfma_f32_16x16x32_bf16 v[146:149], v[150:153], v[166:169], v[146:149]
	ds_read_b64_tr_b16 v[150:151], v95 offset:8192
	ds_read_b64_tr_b16 v[152:153], v94 offset:8192
	v_cndmask_b32_e64 v138, 0, v78, s[46:47]
	v_cndmask_b32_e64 v139, 0, v79, s[40:41]
	s_waitcnt lgkmcnt(2)
	v_mfma_f32_16x16x32_bf16 v[158:161], v[162:165], v[166:169], v[158:161]
	ds_read_b64_tr_b16 v[162:163], v144 offset:16384
	ds_read_b64_tr_b16 v[164:165], v143 offset:16384
	v_cndmask_b32_e64 v140, 0, v80, s[42:43]
	v_cndmask_b32_e64 v145, 0, v81, s[44:45]
	v_mfma_f32_16x16x32_bf16 v[154:157], v[170:173], v[166:169], v[154:157]
	v_cndmask_b32_e64 v174, 0, v82, s[46:47]
	v_cvt_pk_bf16_f32 v170, v84, v85
	v_cvt_pk_bf16_f32 v171, v131, v138
	v_cvt_pk_bf16_f32 v172, v139, v140
	v_cvt_pk_bf16_f32 v173, v145, v174
	v_cndmask_b32_e64 v84, v76, 0, s[42:43]
	v_cndmask_b32_e64 v85, v77, 0, s[44:45]
	v_cndmask_b32_e64 v131, v78, 0, s[46:47]
	s_waitcnt lgkmcnt(2)
; #define GAS __attribute__((address_space(1)))
; __device__ __forceinline__ unsigned cvtpk(float lo, float hi) { return pk2(lo, hi); }
; __device__ __forceinline__ s16x4 vtr(const LAS unsigned char* p) { return __builtin_bit_cast(s16x4, __builtin_amdgcn_ds_read_tr16_b64_v4i16((LAS s16x4*)p)); }
; #define ATT_BIAS_WRITE() do { bias[tid] = bnext[0]; if (tid + 512 < 930) bias[tid + 512] = bnext[1]; } while (0)
; __device__ __forceinline__ void attn_phase(LAS unsigned char* lds, bf16* Qb, const bf16* Kb, const bf16* Vb, const float* rpb_l, int seq_len, int G, int bx, int tid, int wave, int lane) {
;     ...
; #pragma unroll
;         for (int u = 0; u < 4; ++u) {
; #pragma unroll
;             for (int ai = 0; ai < 2; ++ai) {
; #pragma unroll
;                 for (int c = 0; c < 4; ++c) {
;                     const s16x4 v0 = vtr(vb[ai][0][c] + u * 8192), v1 = vtr(vb[ai][1][c] + u * 8192);
;                     const bf16x8 vf = __builtin_shufflevector(v0, v1, 0, 1, 2, 3, 4, 5, 6, 7);
;                     O[c] = __builtin_amdgcn_mfma_f32_16x16x32_bf16(vf, pf[u][ai], O[c], 0, 0, 0);
;                 }
;             }
;         }
;         const float inv = 1.0f / sum;
; #pragma unroll
;         for (int c = 0; c < 4; ++c) { v2u w; w.x = cvtpk(O[c][0] * inv, O[c][1] * inv); w.y = cvtpk(O[c][2] * inv, O[c][3] * inv);
;             *(GAS v2u*)(Qb + qoff + 16 * c + 4 * fq) = w; }
;         if (has_next) ATT_BIAS_WRITE();
	v_mfma_f32_16x16x32_bf16 v[72:75], v[150:153], v[166:169], v[72:75]
	ds_read_b64_tr_b16 v[150:151], v142 offset:16384
	ds_read_b64_tr_b16 v[152:153], v141 offset:16384
	v_cndmask_b32_e64 v138, v79, 0, s[40:41]
	v_cndmask_b32_e64 v83, v83, 0, s[40:41]
	s_waitcnt lgkmcnt(2)
	v_mfma_f32_16x16x32_bf16 v[76:79], v[162:165], v[170:173], v[154:157]
	s_nop 2
	ds_read_b64_tr_b16 v[154:155], v137 offset:16384
	ds_read_b64_tr_b16 v[156:157], v136 offset:16384
	v_cndmask_b32_e64 v139, v80, 0, s[42:43]
	v_cndmask_b32_e64 v140, v81, 0, s[44:45]
	v_cndmask_b32_e64 v145, v82, 0, s[46:47]
	v_cvt_pk_bf16_f32 v162, v83, v84
	s_waitcnt lgkmcnt(2)
	v_mfma_f32_16x16x32_bf16 v[80:83], v[150:153], v[170:173], v[146:149]
	s_nop 2
	ds_read_b64_tr_b16 v[146:147], v135 offset:16384
	ds_read_b64_tr_b16 v[148:149], v134 offset:16384
	v_cvt_pk_bf16_f32 v163, v85, v131
	v_cvt_pk_bf16_f32 v164, v138, v139
	s_waitcnt lgkmcnt(2)
	v_mfma_f32_16x16x32_bf16 v[150:153], v[154:157], v[170:173], v[158:161]
	ds_read_b64_tr_b16 v[154:155], v133 offset:16384
	ds_read_b64_tr_b16 v[156:157], v132 offset:16384
	v_cvt_pk_bf16_f32 v165, v140, v145
	v_cndmask_b32_e64 v131, 0, v92, s[40:41]
	s_waitcnt lgkmcnt(2)
	v_mfma_f32_16x16x32_bf16 v[146:149], v[146:149], v[170:173], v[72:75]
	s_nop 2
	ds_read_b64_tr_b16 v[72:73], v130 offset:16384
	ds_read_b64_tr_b16 v[74:75], v129 offset:16384
	v_cndmask_b32_e64 v138, 0, v93, s[42:43]
	v_cndmask_b32_e64 v139, 0, v89, s[44:45]
	s_waitcnt lgkmcnt(2)
	v_mfma_f32_16x16x32_bf16 v[154:157], v[154:157], v[162:165], v[76:79]
	s_nop 2
	ds_read_b64_tr_b16 v[76:77], v128 offset:16384
	ds_read_b64_tr_b16 v[78:79], v96 offset:16384
	ds_read_b64_tr_b16 v[158:159], v95 offset:16384
	ds_read_b64_tr_b16 v[160:161], v94 offset:16384
	v_cndmask_b32_e64 v140, 0, v90, s[46:47]
	s_waitcnt lgkmcnt(4)
	v_mfma_f32_16x16x32_bf16 v[82:85], v[72:75], v[162:165], v[80:83]
	v_cndmask_b32_e64 v145, 0, v91, s[40:41]
	v_cndmask_b32_e64 v166, 0, v86, s[42:43]
	v_cndmask_b32_e64 v167, 0, v87, s[44:45]
	s_waitcnt lgkmcnt(2)
	v_mfma_f32_16x16x32_bf16 v[78:81], v[76:79], v[162:165], v[150:153]
	s_nop 2
	ds_read_b64_tr_b16 v[150:151], v144 offset:24576
	ds_read_b64_tr_b16 v[152:153], v143 offset:24576
	v_cndmask_b32_e64 v72, 0, v88, s[46:47]
	v_cvt_pk_bf16_f32 v74, v131, v138
	v_cvt_pk_bf16_f32 v75, v139, v140
	v_cvt_pk_bf16_f32 v76, v145, v166
	v_cvt_pk_bf16_f32 v77, v167, v72
	ds_read_b64_tr_b16 v[138:139], v142 offset:24576
	ds_read_b64_tr_b16 v[140:141], v141 offset:24576
	s_waitcnt lgkmcnt(4)
	v_mfma_f32_16x16x32_bf16 v[144:147], v[158:161], v[162:165], v[146:149]
	v_cndmask_b32_e64 v72, v92, 0, s[40:41]
	v_cndmask_b32_e64 v73, v93, 0, s[42:43]
	v_cndmask_b32_e64 v89, v89, 0, s[44:45]
	s_waitcnt lgkmcnt(2)
	v_mfma_f32_16x16x32_bf16 v[148:151], v[150:153], v[74:77], v[154:157]
	ds_read_b64_tr_b16 v[152:153], v137 offset:24576
	s_nop 1
	ds_read_b64_tr_b16 v[154:155], v136 offset:24576
	v_cndmask_b32_e64 v131, v90, 0, s[46:47]
	v_cndmask_b32_e64 v142, v91, 0, s[40:41]
	s_waitcnt lgkmcnt(2)
	v_mfma_f32_16x16x32_bf16 v[90:93], v[138:141], v[74:77], v[82:85]
	ds_read_b64_tr_b16 v[136:137], v135 offset:24576
	ds_read_b64_tr_b16 v[138:139], v134 offset:24576
	v_cndmask_b32_e64 v134, v86, 0, s[42:43]
	v_cndmask_b32_e64 v135, v87, 0, s[44:45]
	s_waitcnt lgkmcnt(2)
	v_mfma_f32_16x16x32_bf16 v[84:87], v[152:155], v[74:77], v[78:81]
	s_nop 2
	ds_read_b64_tr_b16 v[80:81], v133 offset:24576
	ds_read_b64_tr_b16 v[82:83], v132 offset:24576
	v_cvt_pk_bf16_f32 v72, v72, v73
	v_cvt_pk_bf16_f32 v73, v89, v131
	ds_read_b64_tr_b16 v[130:131], v130 offset:24576
	ds_read_b64_tr_b16 v[132:133], v129 offset:24576
	v_cndmask_b32_e64 v88, v88, 0, s[46:47]
	s_lshl_b32 s4, s62, 6
	s_waitcnt lgkmcnt(4)
	v_mfma_f32_16x16x32_bf16 v[76:79], v[136:139], v[74:77], v[144:147]
	v_cvt_pk_bf16_f32 v74, v142, v134
	v_cvt_pk_bf16_f32 v75, v135, v88
	s_add_i32 s4, s63, s4
	v_add_f32_e32 v127, v97, v127
	ds_read_b64_tr_b16 v[134:135], v128 offset:24576
	ds_read_b64_tr_b16 v[136:137], v96 offset:24576
	v_add_u32_e32 v96, s4, v99
	s_waitcnt lgkmcnt(2)
	v_mfma_f32_16x16x32_bf16 v[88:91], v[130:133], v[72:75], v[90:93]
	s_nop 2
	ds_read_b64_tr_b16 v[92:93], v95 offset:24576
	ds_read_b64_tr_b16 v[94:95], v94 offset:24576
	v_div_scale_f32 v128, s[4:5], v127, v127, 1.0
	v_rcp_f32_e32 v129, v128
	v_mfma_f32_16x16x32_bf16 v[80:83], v[80:83], v[72:75], v[148:151]
	v_ashrrev_i32_e32 v97, 31, v96
	s_lshl_b32 s14, s64, 6
	s_ashr_i32 s15, s14, 31
	s_waitcnt lgkmcnt(2)
	v_mfma_f32_16x16x32_bf16 v[84:87], v[134:137], v[72:75], v[84:87]
	v_readlane_b32 s68, v254, 55
	v_readlane_b32 s70, v254, 57
	v_readlane_b32 s69, v254, 56
	s_waitcnt lgkmcnt(0)
	v_mfma_f32_16x16x32_bf16 v[72:75], v[92:95], v[72:75], v[76:79]
	v_readlane_b32 s71, v254, 58
	s_nop 1
	v_fma_f32 v76, -v128, v129, 1.0
	v_fmac_f32_e32 v129, v76, v129
	v_div_scale_f32 v76, vcc, 1.0, v127, 1.0
	v_mul_f32_e32 v77, v76, v129
	v_fma_f32 v78, -v128, v77, v76
	v_fmac_f32_e32 v77, v78, v129
	v_fma_f32 v76, -v128, v77, v76
	v_div_fmas_f32 v76, v76, v129, v77
	v_lshlrev_b64 v[78:79], 11, v[96:97]
	v_div_fixup_f32 v76, v76, v127, 1.0
	v_lshl_add_u64 v[78:79], s[8:9], 0, v[78:79]
	v_lshl_add_u64 v[78:79], s[14:15], 1, v[78:79]
	v_pk_mul_f32 v[80:81], v[76:77], v[80:81] op_sel_hi:[0,1]
	v_pk_mul_f32 v[82:83], v[76:77], v[82:83] op_sel_hi:[0,1]
	v_lshl_add_u64 v[78:79], v[78:79], 0, v[208:209]
	v_cvt_pk_bf16_f32 v80, v80, v81
	v_cvt_pk_bf16_f32 v81, v82, v83
	global_store_dwordx2 v[78:79], v[80:81], off
	v_pk_mul_f32 v[80:81], v[76:77], v[88:89] op_sel_hi:[0,1]
	v_pk_mul_f32 v[82:83], v[76:77], v[90:91] op_sel_hi:[0,1]
	v_cvt_pk_bf16_f32 v80, v80, v81
	v_cvt_pk_bf16_f32 v81, v82, v83
	global_store_dwordx2 v[78:79], v[80:81], off offset:32
	v_pk_mul_f32 v[80:81], v[76:77], v[84:85] op_sel_hi:[0,1]
	v_pk_mul_f32 v[82:83], v[76:77], v[86:87] op_sel_hi:[0,1]
	v_pk_mul_f32 v[72:73], v[76:77], v[72:73] op_sel_hi:[0,1]
	v_pk_mul_f32 v[74:75], v[76:77], v[74:75] op_sel_hi:[0,1]
	v_cvt_pk_bf16_f32 v80, v80, v81
	v_cvt_pk_bf16_f32 v81, v82, v83
	v_cvt_pk_bf16_f32 v72, v72, v73
	v_cvt_pk_bf16_f32 v73, v74, v75
	s_andn2_b64 vcc, exec, s[12:13]
	s_mov_b64 s[12:13], -1
	global_store_dwordx2 v[78:79], v[80:81], off offset:64
	global_store_dwordx2 v[78:79], v[72:73], off offset:96
	s_cbranch_vccnz .LBB0_95
	s_waitcnt vmcnt(4)
	v_mul_f32_e32 v108, 0x3fb8aa3b, v175
	ds_write_b32 v101, v108
	s_and_saveexec_b64 s[12:13], s[38:39]
	s_cbranch_execz .LBB0_94
	v_mul_f32_e32 v105, 0x3fb8aa3b, v176
	ds_write_b32 v101, v105 offset:2048
	s_branch .LBB0_94

; #define PG8_STAGE(bufoff, gbase, voff) do { _Pragma("unroll") for (int _i = 0; _i < 2; ++_i) \
;         __builtin_amdgcn_global_load_lds((const unsigned*)((const char*)(gbase) + (voff)[_i]), (PG8_LAS unsigned*)(lds + (bufoff) + ldsw + _i * 8192), 16, 0, 0); } while (0)
; #define PG8_WAIT_V(n) asm volatile("s_waitcnt vmcnt(" #n ")" ::: "memory")
; #define PG8_BAR __builtin_amdgcn_s_barrier()
; template <class Epi, class Sched, bool ALIGN_EPI = false, bool SP2 = false>
; __device__ __forceinline__ void gemm_phase(PG8_LAS unsigned char* lds, const Gemm g, const Sched& S, const Epi& E, const int tid_in) {
;     ...
;     if constexpr (SP2) {
;         PG8_STAGE(PG8_SB(0, 0), cB, voffB); PG8_STAGE(PG8_SB(0, 1), cB + hstepB, voffB); PG8_STAGE(PG8_SA(0, 0), cA, voffA); PG8_STAGE(PG8_SA(0, 1), cA + hstepA, voffA);
;         if (wr == 1) PG8_BAR;
;         PG8_WAIT_V(2); PG8_BAR;
;         PG8_STAGE(PG8_SB(1, 0), cB + kstepB, voffB); PG8_STAGE(PG8_SA(1, 0), cA + kstepA, voffA); PG8_STAGE(PG8_SB(1, 1), cB + hstepB + kstepB, voffB);
;         PG8_WAIT_V(6); PG8_BAR;
.LBB0_109:
	s_and_b32 s4, s20, 3
	s_lshl_b32 s51, s7, 6
	s_lshl_b32 s20, s7, 13
	s_lshl_b32 s52, s4, 5
	s_lshl_b32 s21, s4, 12
	s_add_u32 s4, s28, 0x4000
	v_mov_b32_e32 v129, v209
	s_addc_u32 s5, s29, 0
	s_add_i32 m0, s11, 0x18000
	v_lshl_add_u64 v[0:1], s[4:5], 0, v[128:129]
	v_mov_b32_e32 v131, v209
	global_load_lds_dwordx4 v[0:1], off
	s_add_i32 m0, s11, 0x1a000
	v_lshl_add_u64 v[0:1], s[4:5], 0, v[130:131]
	s_add_u32 s4, s26, 0x4000
	s_addc_u32 s5, s27, 0
	s_add_i32 s56, s11, 0x8000
	global_load_lds_dwordx4 v[0:1], off
	v_lshl_add_u64 v[0:1], s[4:5], 0, v[128:129]
	s_mov_b32 m0, s56
	s_add_i32 s57, s11, 0xa000
	global_load_lds_dwordx4 v[0:1], off
	v_lshl_add_u64 v[0:1], s[4:5], 0, v[130:131]
	s_add_u32 s4, s18, 0x4000
	s_mov_b32 m0, s57
	s_addc_u32 s5, s19, 0
	global_load_lds_dwordx4 v[0:1], off
	s_add_i32 m0, s11, 0x1c000
	v_lshl_add_u64 v[0:1], s[4:5], 0, v[128:129]
	global_load_lds_dwordx4 v[0:1], off
	v_lshl_add_u64 v[0:1], s[4:5], 0, v[130:131]
	s_add_i32 m0, s11, 0x1e000
	s_cmp_gt_i32 s9, 63
	global_load_lds_dwordx4 v[0:1], off
	s_waitcnt vmcnt(8)
	s_barrier
	v_and_b32_e32 v136, 48, v188
	v_and_b32_e32 v137, 15, v188
	v_lshlrev_b32_e32 v1, 2, v188
	s_cselect_b64 s[18:19], -1, 0
	s_add_i32 s58, s10, -2
	v_lshl_or_b32 v0, v137, 6, v136
	v_and_b32_e32 v1, 32, v1
	s_cmpk_lt_u32 s6, 0x100
	v_bitop3_b32 v2, v0, s20, v1 bitop3:0xde
	v_bitop3_b32 v138, s21, v0, v1 bitop3:0xf6
	s_cselect_b64 s[20:21], -1, 0
	s_lshl_b32 s4, s7, 3
	s_waitcnt vmcnt(6)
	s_and_b32 s4, s4, 8
	s_bfe_u32 s61, s6, 0x10006
	s_or_b32 s4, s4, s61
	s_bfe_u32 s59, s7, 0x10001
	s_ashr_i32 s60, s53, 31
	s_ashr_i32 s9, s8, 31
	s_lshl_b32 s62, s4, 10
	v_lshl_add_u64 v[132:133], s[12:13], 0, v[128:129]
	v_lshl_add_u64 v[134:135], s[12:13], 0, v[130:131]
	s_mov_b32 s63, 0
	v_add_u32_e32 v139, 0, v2
	s_barrier
	s_branch .LBB0_112

;     __host__ __device__ bool next(int i, Unit& u) const {
;         long L = (long)i * G + c; if (L >= nwg) return false;
;         if (rev) L = nwg - 1 - L;
;         int wgid = (int)L; { const int q = nwg / NXCD, r = nwg % NXCD, xcd = wgid % NXCD, off = wgid / NXCD; wgid = (xcd < r ? xcd * (q + 1) : r * (q + 1) + (xcd - r) * q) + off; }
;         const int nig = WGM * nN, gid = wgid / nig, fm = gid * WGM, gsz = (nM - fm) < WGM ? (nM - fm) : WGM;
;         u.pm = fm + ((wgid % nig) % gsz); u.pn = (wgid % nig) / gsz; return true;
;     }
; template <class Epi, class Sched, bool ALIGN_EPI = false, bool SP2 = false>
; __device__ __forceinline__ void gemm_phase(PG8_LAS unsigned char* lds, const Gemm g, const Sched& S, const Epi& E, const int tid_in) {
;     ...
;         const bool has_next = S.next(ui + 1, nxt);
.LBB0_112:
	s_add_i32 s63, s63, 1
	s_mul_i32 s4, s63, s60
	s_mul_hi_u32 s5, s63, s53
	s_add_i32 s5, s5, s4
	s_mul_i32 s4, s63, s53
	s_add_u32 s22, s4, s2
	s_addc_u32 s23, s5, s3
	v_mov_b64_e32 v[0:1], s[8:9]
	v_cmp_ge_i64_e32 vcc, s[22:23], v[0:1]
	v_cmp_lt_i64_e64 s[40:41], s[22:23], v[0:1]
	s_cbranch_vccnz .LBB0_114
	v_readlane_b32 s4, v255, 20
	s_cmp_lg_u32 s4, 0
	s_cbranch_scc0 .Lnx_up_gen
	s_lshl_b32 s4, s63, 5
	s_lshr_b32 s5, s2, 3
	s_add_i32 s4, s4, s5
	s_cmp_ge_u32 s4, s33
	s_cselect_b32 s5, s33, 0
	s_cselect_b32 s6, 8, 0
	s_sub_i32 s4, s4, s5
	s_and_b32 s5, s2, 7
	s_lshl_b32 s5, s5, 4
	s_add_i32 s5, s5, s6
	s_and_b32 s6, s4, 7
	s_add_i32 s68, s5, s6
	s_lshr_b32 s64, s4, 3
	s_branch .LBB0_114
.Lnx_up_gen:
	s_ashr_i32 s4, s22, 31
	s_lshr_b32 s4, s4, 29
	s_add_i32 s4, s22, s4
	s_ashr_i32 s5, s4, 3
	s_and_b32 s4, s4, -8
	s_sub_i32 s4, s22, s4
	s_lshr_b32 s6, s4, 31
	s_or_b32 s6, s1, s6
	s_mul_i32 s4, s6, s4
	s_add_i32 s4, s4, s5
	s_abs_i32 s6, s4
	s_mul_hi_u32 s7, s6, s43
	s_mul_i32 s22, s7, s37
	s_ashr_i32 s5, s4, 31
	s_sub_i32 s6, s6, s22
	s_xor_b32 s5, s5, s42
	s_add_i32 s22, s7, 1
	s_sub_i32 s23, s6, s37
	s_cmp_ge_u32 s6, s37
	s_cselect_b32 s7, s22, s7
	s_cselect_b32 s6, s23, s6
	s_add_i32 s22, s7, 1
	s_cmp_ge_u32 s6, s37
	s_cselect_b32 s6, s22, s7
	s_xor_b32 s6, s6, s5
	s_sub_i32 s5, s6, s5
	s_lshl_b32 s6, s5, 3
	s_sub_i32 s7, 0x80, s6
	s_min_i32 s7, s7, 8
	s_abs_i32 s22, s7
	v_cvt_f32_u32_e32 v0, s22
	s_sub_i32 s24, 0, s22
	s_mul_i32 s5, s5, s33
	s_sub_i32 s4, s4, s5
	v_rcp_iflag_f32_e32 v0, v0
	s_abs_i32 s23, s4
	s_xor_b32 s5, s4, s7
	s_ashr_i32 s5, s5, 31
	v_mul_f32_e32 v0, 0x4f7ffffe, v0
	v_cvt_u32_f32_e32 v0, v0
	s_nop 0
	v_readfirstlane_b32 s25, v0
	s_mul_i32 s24, s24, s25
	s_mul_hi_u32 s24, s25, s24
	s_add_i32 s25, s25, s24
	s_mul_hi_u32 s24, s23, s25
	s_mul_i32 s25, s24, s22
	s_sub_i32 s23, s23, s25
	s_add_i32 s25, s24, 1
	s_sub_i32 s30, s23, s22
	s_cmp_ge_u32 s23, s22
	s_cselect_b32 s24, s25, s24
	s_cselect_b32 s23, s30, s23
	s_add_i32 s25, s24, 1
	s_cmp_ge_u32 s23, s22
	s_cselect_b32 s22, s25, s24
	s_xor_b32 s22, s22, s5
	s_sub_i32 s64, s22, s5
	s_mul_i32 s5, s64, s7
	s_sub_i32 s4, s4, s5
	s_add_i32 s68, s4, s6

; __device__ __forceinline__ unsigned cvt_pk_bf16(float lo, float hi) { unsigned r; asm volatile("v_cvt_pk_bf16_f32 %0, %1, %2" : "=v"(r) : "v"(lo), "v"(hi)); return r; }
;     __device__ __forceinline__ void operator()(const f32x4 (&acc)[2][2][4][2], const Unit& u, int wr, int wc, int fr, int fq) const {
;     ...
;                 for (int bj = 0; bj < 2; ++bj) { f32x4 v0 = acc[ai][bj][m][0], v1 = acc[ai][bj][m][1];
;                     if (ACT == 2) {
; #pragma unroll
;                         for (int e = 0; e < 4; ++e) { const float a = fmaxf(v0[e], 0.f), b = fmaxf(v1[e], 0.f); v0[e] = a * a; v1[e] = b * b; } }
;                     v0 = v0 * f; v1 = v1 * f; u32x4 w; w.x = cvt_pk_bf16(v0[0], v0[1]); w.y = cvt_pk_bf16(v0[2], v0[3]); w.z = cvt_pk_bf16(v1[0], v1[1]); w.w = cvt_pk_bf16(v1[2], v1[3]);
;                     if (kplane) *(u32x4*)(base + ((size_t)(((colt >> 6) + 2 * bj + (wc >> 1)) * 8 + (wc & 1) * 4 + fq) * kprows + row) * 8) = w;
;                     else if (tiled) { const int r_ = row & 255, c_ = col0 + bj * HALF;
;                         *(u32x4*)((char*)base + ((size_t)(((row >> 8) * 2 + (r_ >> 7)) * (ldc >> 6) + (c_ >> 6)) << 14) + lds_byte(r_ & 127, c_ & 63)) = w; }
;                     else *(u32x4*)(rowp + bj * HALF) = w; } }
.LBB0_123:
	s_lshl_b32 s30, s70, 8
	s_add_i32 s30, s30, s51
	s_ashr_i32 s5, s30, 7
	s_lshl_b32 s4, s69, 8
	s_and_b32 s5, s5, 0x3fffffe
	v_or_b32_e32 v140, s30, v137
	s_or_b32 s4, s4, s52
	s_or_b32 s5, s5, s59
	v_lshlrev_b32_e32 v141, 6, v140
	v_lshlrev_b32_e32 v142, 2, v140
	s_lshl_b32 s28, s5, 6
	s_ashr_i32 s6, s4, 6
	v_and_or_b32 v141, v141, s91, v136
	v_and_b32_e32 v144, 32, v142
	v_max_f32_e32 v120, 0, v120
	v_max_f32_e32 v124, 0, v124
	v_max_f32_e32 v121, 0, v121
	v_max_f32_e32 v125, 0, v125
	v_max_f32_e32 v122, 0, v122
	s_add_i32 s4, s28, s6
	v_bitop3_b32 v208, v141, s62, v144 bitop3:0xde
	v_max_f32_e32 v123, 0, v123
	s_ashr_i32 s5, s4, 31
	s_or_b32 s7, s6, 2
	v_lshl_add_u64 v[142:143], s[46:47], 0, v[208:209]
	v_mul_f32_e32 v120, v120, v120
	v_mul_f32_e32 v124, v124, v124
	v_mul_f32_e32 v121, v121, v121
	v_mul_f32_e32 v125, v125, v125
	v_max_f32_e32 v126, 0, v126
	v_mul_f32_e32 v122, v122, v122
	v_max_f32_e32 v127, 0, v127
	s_lshl_b64 s[26:27], s[4:5], 14
	v_max_f32_e32 v112, 0, v112
	v_max_f32_e32 v113, 0, v113
	v_max_f32_e32 v114, 0, v114
	s_add_i32 s4, s7, s28
	v_mul_f32_e32 v123, v123, v123
	v_cvt_pk_bf16_f32 v120, v120, v121
	v_cvt_pk_bf16_f32 v121, v122, v123
	v_cvt_pk_bf16_f32 v122, v124, v125
	v_lshl_add_u64 v[124:125], v[142:143], 0, s[26:27]
	s_ashr_i32 s5, s4, 31
	v_mul_f32_e32 v126, v126, v126
	v_mul_f32_e32 v127, v127, v127
	v_cvt_pk_bf16_f32 v123, v126, v127
	global_store_dwordx4 v[124:125], v[120:123], off
	v_max_f32_e32 v116, 0, v116
	s_lshl_b64 s[28:29], s[4:5], 14
	v_mul_f32_e32 v120, v112, v112
	v_max_f32_e32 v112, 0, v117
	v_mul_f32_e32 v117, v113, v113
	v_max_f32_e32 v113, 0, v118
	v_mul_f32_e32 v118, v114, v114
	v_max_f32_e32 v114, 0, v119
	s_or_b32 s4, s30, 16
	v_max_f32_e32 v115, 0, v115
	s_lshr_b32 s4, s4, 3
	v_mul_f32_e32 v116, v116, v116
	v_mul_f32_e32 v112, v112, v112
	v_mul_f32_e32 v113, v113, v113
	v_mul_f32_e32 v114, v114, v114
	s_and_b32 s4, s4, 10
	v_max_f32_e32 v104, 0, v104
	v_max_f32_e32 v105, 0, v105
	v_max_f32_e32 v106, 0, v106
	v_mul_f32_e32 v115, v115, v115
	v_cvt_pk_bf16_f32 v112, v116, v112
	v_cvt_pk_bf16_f32 v113, v113, v114
	v_cvt_pk_bf16_f32 v114, v120, v117
	v_lshl_add_u64 v[116:117], v[142:143], 0, s[28:29]
	s_or_b32 s4, s4, s61
	v_cvt_pk_bf16_f32 v115, v118, v115
	global_store_dwordx4 v[116:117], v[112:115], off
	s_lshl_b32 s4, s4, 10
	v_max_f32_e32 v108, 0, v108
	v_mul_f32_e32 v114, v104, v104
	v_max_f32_e32 v104, 0, v109
	v_mul_f32_e32 v109, v105, v105
	v_max_f32_e32 v105, 0, v110
	v_mul_f32_e32 v110, v106, v106
	v_max_f32_e32 v106, 0, v111
	v_bitop3_b32 v208, v141, s4, v144 bitop3:0xde
	v_max_f32_e32 v107, 0, v107
	v_lshl_add_u64 v[112:113], s[46:47], 0, v[208:209]
	v_mul_f32_e32 v108, v108, v108
	v_mul_f32_e32 v104, v104, v104
	v_mul_f32_e32 v105, v105, v105
	v_mul_f32_e32 v106, v106, v106
	v_max_f32_e32 v96, 0, v96
	v_max_f32_e32 v97, 0, v97
	v_max_f32_e32 v98, 0, v98
	v_mul_f32_e32 v107, v107, v107
	v_cvt_pk_bf16_f32 v104, v108, v104
	v_cvt_pk_bf16_f32 v105, v105, v106
	v_cvt_pk_bf16_f32 v106, v114, v109
	v_lshl_add_u64 v[108:109], v[112:113], 0, s[26:27]
	v_cvt_pk_bf16_f32 v107, v110, v107
	global_store_dwordx4 v[108:109], v[104:107], off
	v_max_f32_e32 v100, 0, v100
	s_or_b32 s4, s30, 32
	v_mul_f32_e32 v104, v96, v96
	v_max_f32_e32 v96, 0, v101
	v_mul_f32_e32 v101, v97, v97
	v_max_f32_e32 v97, 0, v102
	v_mul_f32_e32 v102, v98, v98
	v_max_f32_e32 v98, 0, v103
	v_max_f32_e32 v99, 0, v99
	s_lshr_b32 s4, s4, 3
	v_mul_f32_e32 v100, v100, v100
	v_mul_f32_e32 v96, v96, v96
	v_mul_f32_e32 v97, v97, v97
	v_mul_f32_e32 v98, v98, v98
	s_and_b32 s4, s4, 12
	v_max_f32_e32 v88, 0, v88
	v_max_f32_e32 v89, 0, v89
	v_max_f32_e32 v90, 0, v90
	v_mul_f32_e32 v99, v99, v99
	v_cvt_pk_bf16_f32 v96, v100, v96
	v_cvt_pk_bf16_f32 v97, v97, v98
	v_cvt_pk_bf16_f32 v98, v104, v101
	v_lshl_add_u64 v[100:101], v[112:113], 0, s[28:29]
	s_or_b32 s4, s4, s61
	v_cvt_pk_bf16_f32 v99, v102, v99
	global_store_dwordx4 v[100:101], v[96:99], off
	s_lshl_b32 s4, s4, 10
	v_max_f32_e32 v92, 0, v92
	v_mul_f32_e32 v98, v88, v88
	v_max_f32_e32 v88, 0, v93
	v_mul_f32_e32 v93, v89, v89
	v_max_f32_e32 v89, 0, v94
	v_mul_f32_e32 v94, v90, v90
	v_max_f32_e32 v90, 0, v95
	v_bitop3_b32 v208, v141, s4, v144 bitop3:0xde
	v_max_f32_e32 v91, 0, v91
	v_lshl_add_u64 v[96:97], s[46:47], 0, v[208:209]
	v_mul_f32_e32 v92, v92, v92
	v_mul_f32_e32 v88, v88, v88
	v_mul_f32_e32 v89, v89, v89
	v_mul_f32_e32 v90, v90, v90
	v_max_f32_e32 v80, 0, v80
	v_max_f32_e32 v81, 0, v81
	v_max_f32_e32 v82, 0, v82
	v_mul_f32_e32 v91, v91, v91
	v_cvt_pk_bf16_f32 v88, v92, v88
	v_cvt_pk_bf16_f32 v89, v89, v90
	v_cvt_pk_bf16_f32 v90, v98, v93
	v_lshl_add_u64 v[92:93], v[96:97], 0, s[26:27]
	v_cvt_pk_bf16_f32 v91, v94, v91
	global_store_dwordx4 v[92:93], v[88:91], off
	v_max_f32_e32 v84, 0, v84
	s_or_b32 s4, s30, 48
	v_mul_f32_e32 v88, v80, v80
	v_max_f32_e32 v80, 0, v85
	v_mul_f32_e32 v85, v81, v81
	v_max_f32_e32 v81, 0, v86
	v_mul_f32_e32 v86, v82, v82
	v_max_f32_e32 v82, 0, v87
	v_max_f32_e32 v83, 0, v83
	s_lshr_b32 s4, s4, 3
	v_mul_f32_e32 v84, v84, v84
	v_mul_f32_e32 v80, v80, v80
	v_mul_f32_e32 v81, v81, v81
	v_mul_f32_e32 v82, v82, v82
	s_and_b32 s4, s4, 14
	v_max_f32_e32 v72, 0, v72
	v_max_f32_e32 v73, 0, v73
	v_max_f32_e32 v74, 0, v74
	v_mul_f32_e32 v83, v83, v83
	v_cvt_pk_bf16_f32 v80, v84, v80
	v_cvt_pk_bf16_f32 v81, v81, v82
	v_cvt_pk_bf16_f32 v82, v88, v85
	v_lshl_add_u64 v[84:85], v[96:97], 0, s[28:29]
	s_or_b32 s4, s4, s61
	v_cvt_pk_bf16_f32 v83, v86, v83
	global_store_dwordx4 v[84:85], v[80:83], off
	s_lshl_b32 s4, s4, 10
	v_max_f32_e32 v76, 0, v76
	v_mul_f32_e32 v82, v72, v72
	v_max_f32_e32 v72, 0, v77
	v_mul_f32_e32 v77, v73, v73
; __device__ __forceinline__ unsigned cvt_pk_bf16(float lo, float hi) { unsigned r; asm volatile("v_cvt_pk_bf16_f32 %0, %1, %2" : "=v"(r) : "v"(lo), "v"(hi)); return r; }
;     __device__ __forceinline__ void operator()(const f32x4 (&acc)[2][2][4][2], const Unit& u, int wr, int wc, int fr, int fq) const {
;     ...
;                 for (int bj = 0; bj < 2; ++bj) { f32x4 v0 = acc[ai][bj][m][0], v1 = acc[ai][bj][m][1];
;                     if (ACT == 2) {
; #pragma unroll
;                         for (int e = 0; e < 4; ++e) { const float a = fmaxf(v0[e], 0.f), b = fmaxf(v1[e], 0.f); v0[e] = a * a; v1[e] = b * b; } }
;                     v0 = v0 * f; v1 = v1 * f; u32x4 w; w.x = cvt_pk_bf16(v0[0], v0[1]); w.y = cvt_pk_bf16(v0[2], v0[3]); w.z = cvt_pk_bf16(v1[0], v1[1]); w.w = cvt_pk_bf16(v1[2], v1[3]);
;                     if (kplane) *(u32x4*)(base + ((size_t)(((colt >> 6) + 2 * bj + (wc >> 1)) * 8 + (wc & 1) * 4 + fq) * kprows + row) * 8) = w;
;                     else if (tiled) { const int r_ = row & 255, c_ = col0 + bj * HALF;
;                         *(u32x4*)((char*)base + ((size_t)(((row >> 8) * 2 + (r_ >> 7)) * (ldc >> 6) + (c_ >> 6)) << 14) + lds_byte(r_ & 127, c_ & 63)) = w; }
;                     else *(u32x4*)(rowp + bj * HALF) = w; } }
	v_max_f32_e32 v73, 0, v78
	v_mul_f32_e32 v78, v74, v74
	v_max_f32_e32 v74, 0, v79
	v_bitop3_b32 v208, v141, s4, v144 bitop3:0xde
	v_max_f32_e32 v75, 0, v75
	v_lshl_add_u64 v[80:81], s[46:47], 0, v[208:209]
	v_mul_f32_e32 v76, v76, v76
	v_mul_f32_e32 v72, v72, v72
	v_mul_f32_e32 v73, v73, v73
	v_mul_f32_e32 v74, v74, v74
	v_max_f32_e32 v64, 0, v64
	v_max_f32_e32 v65, 0, v65
	v_max_f32_e32 v66, 0, v66
	v_mul_f32_e32 v75, v75, v75
	v_cvt_pk_bf16_f32 v72, v76, v72
	v_cvt_pk_bf16_f32 v73, v73, v74
	v_cvt_pk_bf16_f32 v74, v82, v77
	v_lshl_add_u64 v[76:77], v[80:81], 0, s[26:27]
	v_cvt_pk_bf16_f32 v75, v78, v75
	global_store_dwordx4 v[76:77], v[72:75], off
	v_max_f32_e32 v68, 0, v68
	s_nop 0
	v_mul_f32_e32 v72, v64, v64
	v_max_f32_e32 v64, 0, v69
	v_mul_f32_e32 v69, v65, v65
	v_max_f32_e32 v65, 0, v70
	v_mul_f32_e32 v70, v66, v66
	v_max_f32_e32 v66, 0, v71
	v_max_f32_e32 v67, 0, v67
	v_mul_f32_e32 v68, v68, v68
	v_mul_f32_e32 v64, v64, v64
	v_mul_f32_e32 v65, v65, v65
	v_mul_f32_e32 v66, v66, v66
	v_mul_f32_e32 v67, v67, v67
	v_cvt_pk_bf16_f32 v64, v68, v64
	v_cvt_pk_bf16_f32 v65, v65, v66
	v_cvt_pk_bf16_f32 v66, v72, v69
	v_lshl_add_u64 v[68:69], v[80:81], 0, s[28:29]
	v_max_f32_e32 v56, 0, v56
	v_cvt_pk_bf16_f32 v67, v70, v67
	global_store_dwordx4 v[68:69], v[64:67], off
	v_max_f32_e32 v57, 0, v57
	s_nop 0
	v_add_u32_e32 v64, 0x80, v140
	v_max_f32_e32 v58, 0, v58
	v_ashrrev_i32_e32 v65, 7, v64
	v_bfe_u32 v66, v64, 7, 1
	s_mov_b32 s4, 0x3fffffe
	v_max_f32_e32 v60, 0, v60
	v_mul_f32_e32 v67, v56, v56
	v_max_f32_e32 v56, 0, v61
	v_and_or_b32 v66, v65, s4, v66
	v_mul_f32_e32 v61, v57, v57
	v_max_f32_e32 v57, 0, v62
	v_mul_f32_e32 v62, v58, v58
	v_max_f32_e32 v58, 0, v63
	v_lshlrev_b32_e32 v65, 6, v64
	v_lshlrev_b32_e32 v64, 2, v64
	v_mul_f32_e32 v60, v60, v60
	v_mul_f32_e32 v56, v56, v56
	v_lshlrev_b32_e32 v66, 6, v66
	v_and_or_b32 v65, v65, s91, v136
	v_and_b32_e32 v64, 32, v64
	v_mul_f32_e32 v57, v57, v57
	v_max_f32_e32 v59, 0, v59
	v_mul_f32_e32 v58, v58, v58
	v_cvt_pk_bf16_f32 v56, v60, v56
	v_add_u32_e32 v60, s6, v66
	v_bitop3_b32 v208, v65, s62, v64 bitop3:0xde
	v_cvt_pk_bf16_f32 v57, v57, v58
	v_cvt_pk_bf16_f32 v58, v67, v61
	v_ashrrev_i32_e32 v61, 31, v60
	v_lshl_add_u64 v[64:65], s[46:47], 0, v[208:209]
	v_mul_f32_e32 v59, v59, v59
	v_lshlrev_b64 v[60:61], 14, v[60:61]
	v_max_f32_e32 v48, 0, v48
	v_cvt_pk_bf16_f32 v59, v62, v59
	v_lshl_add_u64 v[62:63], v[64:65], 0, v[60:61]
	v_max_f32_e32 v49, 0, v49
	v_max_f32_e32 v50, 0, v50
	global_store_dwordx4 v[62:63], v[56:59], off
	v_max_f32_e32 v52, 0, v52
	s_nop 0
	v_mul_f32_e32 v56, v48, v48
	v_max_f32_e32 v48, 0, v53
	v_mul_f32_e32 v53, v49, v49
	v_max_f32_e32 v49, 0, v54
	v_mul_f32_e32 v54, v50, v50
	v_max_f32_e32 v50, 0, v55
	v_mul_f32_e32 v52, v52, v52
	v_mul_f32_e32 v48, v48, v48
	v_mul_f32_e32 v49, v49, v49
	v_max_f32_e32 v51, 0, v51
	v_mul_f32_e32 v50, v50, v50
	v_cvt_pk_bf16_f32 v48, v52, v48
	v_add_u32_e32 v52, s7, v66
	v_cvt_pk_bf16_f32 v49, v49, v50
	v_cvt_pk_bf16_f32 v50, v56, v53
	v_ashrrev_i32_e32 v53, 31, v52
	v_mul_f32_e32 v51, v51, v51
	v_lshlrev_b64 v[52:53], 14, v[52:53]
	v_cvt_pk_bf16_f32 v51, v54, v51
	v_lshl_add_u64 v[54:55], v[64:65], 0, v[52:53]
	global_store_dwordx4 v[54:55], v[48:51], off
	v_max_f32_e32 v40, 0, v40
	v_max_f32_e32 v41, 0, v41
	v_add_u32_e32 v48, 0x90, v140
	v_lshrrev_b32_e32 v49, 3, v48
	v_and_or_b32 v49, v49, 10, s61
	v_lshlrev_b32_e32 v50, 6, v48
	v_lshlrev_b32_e32 v48, 2, v48
	v_max_f32_e32 v42, 0, v42
	v_and_or_b32 v50, v50, s91, v136
	v_lshlrev_b32_e32 v49, 10, v49
	v_and_b32_e32 v48, 32, v48
	v_bitop3_b32 v208, v50, v49, v48 bitop3:0xde
	v_max_f32_e32 v44, 0, v44
	v_mul_f32_e32 v50, v40, v40
	v_max_f32_e32 v40, 0, v45
	v_mul_f32_e32 v45, v41, v41
	v_max_f32_e32 v41, 0, v46
	v_mul_f32_e32 v46, v42, v42
	v_max_f32_e32 v42, 0, v47
	v_max_f32_e32 v43, 0, v43
	v_lshl_add_u64 v[48:49], s[46:47], 0, v[208:209]
	v_mul_f32_e32 v44, v44, v44
	v_mul_f32_e32 v40, v40, v40
	v_mul_f32_e32 v41, v41, v41
	v_mul_f32_e32 v42, v42, v42
	v_max_f32_e32 v32, 0, v32
	v_max_f32_e32 v33, 0, v33
	v_max_f32_e32 v34, 0, v34
	v_mul_f32_e32 v43, v43, v43
	v_cvt_pk_bf16_f32 v40, v44, v40
	v_cvt_pk_bf16_f32 v41, v41, v42
	v_cvt_pk_bf16_f32 v42, v50, v45
; __device__ __forceinline__ unsigned cvt_pk_bf16(float lo, float hi) { unsigned r; asm volatile("v_cvt_pk_bf16_f32 %0, %1, %2" : "=v"(r) : "v"(lo), "v"(hi)); return r; }
; #define PG8_BAR __builtin_amdgcn_s_barrier()
;     __device__ __forceinline__ void operator()(const f32x4 (&acc)[2][2][4][2], const Unit& u, int wr, int wc, int fr, int fq) const {
;     ...
;                 for (int bj = 0; bj < 2; ++bj) { f32x4 v0 = acc[ai][bj][m][0], v1 = acc[ai][bj][m][1];
;                     if (ACT == 2) {
; #pragma unroll
;                         for (int e = 0; e < 4; ++e) { const float a = fmaxf(v0[e], 0.f), b = fmaxf(v1[e], 0.f); v0[e] = a * a; v1[e] = b * b; } }
;                     v0 = v0 * f; v1 = v1 * f; u32x4 w; w.x = cvt_pk_bf16(v0[0], v0[1]); w.y = cvt_pk_bf16(v0[2], v0[3]); w.z = cvt_pk_bf16(v1[0], v1[1]); w.w = cvt_pk_bf16(v1[2], v1[3]);
;                     if (kplane) *(u32x4*)(base + ((size_t)(((colt >> 6) + 2 * bj + (wc >> 1)) * 8 + (wc & 1) * 4 + fq) * kprows + row) * 8) = w;
;                     else if (tiled) { const int r_ = row & 255, c_ = col0 + bj * HALF;
;                         *(u32x4*)((char*)base + ((size_t)(((row >> 8) * 2 + (r_ >> 7)) * (ldc >> 6) + (c_ >> 6)) << 14) + lds_byte(r_ & 127, c_ & 63)) = w; }
;                     else *(u32x4*)(rowp + bj * HALF) = w; } }
; template <class Epi, class Sched, bool ALIGN_EPI = false, bool SP2 = false>
; __device__ __forceinline__ void gemm_phase(PG8_LAS unsigned char* lds, const Gemm g, const Sched& S, const Epi& E, const int tid_in) {
;     ...
;         if constexpr (ALIGN_EPI) { if (wr == 0) PG8_BAR; }
;         if constexpr (!Epi::AFTER_DRAIN) { E(acc, cur, wr, wc, fr, fq); S.done(cur); }
;         if (!has_next) break;
; #pragma unroll
;         for (int a = 0; a < 2; ++a)
; #pragma unroll
;             for (int b = 0; b < 2; ++b)
; #pragma unroll
;                 for (int m = 0; m < 4; ++m)
; #pragma unroll
;                     for (int n = 0; n < 2; ++n) acc[a][b][m][n] = (f32x4){0.f, 0.f, 0.f, 0.f};
;         cur = nxt; cA = nA; cB = nB; ++ui;
;         if constexpr (ALIGN_EPI) { if (wr == 1) PG8_BAR; }
	v_lshl_add_u64 v[44:45], v[48:49], 0, v[60:61]
	v_cvt_pk_bf16_f32 v43, v46, v43
	global_store_dwordx4 v[44:45], v[40:43], off
	v_max_f32_e32 v36, 0, v36
	s_nop 0
	v_mul_f32_e32 v40, v32, v32
	v_max_f32_e32 v32, 0, v37
	v_mul_f32_e32 v37, v33, v33
	v_max_f32_e32 v33, 0, v38
	v_mul_f32_e32 v38, v34, v34
	v_max_f32_e32 v34, 0, v39
	v_max_f32_e32 v35, 0, v35
	v_mul_f32_e32 v36, v36, v36
	v_mul_f32_e32 v32, v32, v32
	v_mul_f32_e32 v33, v33, v33
	v_mul_f32_e32 v34, v34, v34
	v_mul_f32_e32 v35, v35, v35
	v_cvt_pk_bf16_f32 v32, v36, v32
	v_cvt_pk_bf16_f32 v33, v33, v34
	v_cvt_pk_bf16_f32 v34, v40, v37
	v_lshl_add_u64 v[36:37], v[48:49], 0, v[52:53]
	v_cvt_pk_bf16_f32 v35, v38, v35
	global_store_dwordx4 v[36:37], v[32:35], off
	v_max_f32_e32 v24, 0, v24
	v_max_f32_e32 v25, 0, v25
	v_add_u32_e32 v32, 0xa0, v140
	v_lshrrev_b32_e32 v33, 3, v32
	v_and_or_b32 v33, v33, 12, s61
	v_lshlrev_b32_e32 v34, 6, v32
	v_lshlrev_b32_e32 v32, 2, v32
	v_max_f32_e32 v26, 0, v26
	v_and_or_b32 v34, v34, s91, v136
	v_lshlrev_b32_e32 v33, 10, v33
	v_and_b32_e32 v32, 32, v32
	v_bitop3_b32 v208, v34, v33, v32 bitop3:0xde
	v_max_f32_e32 v28, 0, v28
	v_mul_f32_e32 v34, v24, v24
	v_max_f32_e32 v24, 0, v29
	v_mul_f32_e32 v29, v25, v25
	v_max_f32_e32 v25, 0, v30
	v_mul_f32_e32 v30, v26, v26
	v_max_f32_e32 v26, 0, v31
	v_max_f32_e32 v27, 0, v27
	v_lshl_add_u64 v[32:33], s[46:47], 0, v[208:209]
	v_mul_f32_e32 v28, v28, v28
	v_mul_f32_e32 v24, v24, v24
	v_mul_f32_e32 v25, v25, v25
	v_mul_f32_e32 v26, v26, v26
	v_max_f32_e32 v16, 0, v16
	v_max_f32_e32 v17, 0, v17
	v_max_f32_e32 v18, 0, v18
	v_mul_f32_e32 v27, v27, v27
	v_cvt_pk_bf16_f32 v24, v28, v24
	v_cvt_pk_bf16_f32 v25, v25, v26
	v_cvt_pk_bf16_f32 v26, v34, v29
	v_lshl_add_u64 v[28:29], v[32:33], 0, v[60:61]
	v_cvt_pk_bf16_f32 v27, v30, v27
	global_store_dwordx4 v[28:29], v[24:27], off
	v_max_f32_e32 v20, 0, v20
	s_nop 0
	v_mul_f32_e32 v24, v16, v16
	v_max_f32_e32 v16, 0, v21
	v_mul_f32_e32 v21, v17, v17
	v_max_f32_e32 v17, 0, v22
	v_mul_f32_e32 v22, v18, v18
	v_max_f32_e32 v18, 0, v23
	v_max_f32_e32 v19, 0, v19
	v_mul_f32_e32 v20, v20, v20
	v_mul_f32_e32 v16, v16, v16
	v_mul_f32_e32 v17, v17, v17
	v_mul_f32_e32 v18, v18, v18
	v_mul_f32_e32 v19, v19, v19
	v_cvt_pk_bf16_f32 v16, v20, v16
	v_cvt_pk_bf16_f32 v17, v17, v18
	v_cvt_pk_bf16_f32 v18, v24, v21
	v_lshl_add_u64 v[20:21], v[32:33], 0, v[52:53]
	v_cvt_pk_bf16_f32 v19, v22, v19
	global_store_dwordx4 v[20:21], v[16:19], off
	v_max_f32_e32 v8, 0, v8
	v_max_f32_e32 v9, 0, v9
	v_add_u32_e32 v16, 0xb0, v140
	v_lshrrev_b32_e32 v17, 3, v16
	v_and_or_b32 v17, v17, 14, s61
	v_lshlrev_b32_e32 v18, 6, v16
	v_lshlrev_b32_e32 v16, 2, v16
	v_max_f32_e32 v10, 0, v10
	v_and_or_b32 v18, v18, s91, v136
	v_lshlrev_b32_e32 v17, 10, v17
	v_and_b32_e32 v16, 32, v16
	v_bitop3_b32 v208, v18, v17, v16 bitop3:0xde
	v_max_f32_e32 v12, 0, v12
	v_mul_f32_e32 v18, v8, v8
	v_max_f32_e32 v8, 0, v13
	v_mul_f32_e32 v13, v9, v9
	v_max_f32_e32 v9, 0, v14
	v_mul_f32_e32 v14, v10, v10
	v_max_f32_e32 v10, 0, v15
	v_max_f32_e32 v11, 0, v11
	v_lshl_add_u64 v[16:17], s[46:47], 0, v[208:209]
	v_mul_f32_e32 v12, v12, v12
	v_mul_f32_e32 v8, v8, v8
	v_mul_f32_e32 v9, v9, v9
	v_mul_f32_e32 v10, v10, v10
	v_max_f32_e32 v0, 0, v0
	v_max_f32_e32 v1, 0, v1
	v_max_f32_e32 v2, 0, v2
	v_mul_f32_e32 v11, v11, v11
	v_cvt_pk_bf16_f32 v8, v12, v8
	v_cvt_pk_bf16_f32 v9, v9, v10
	v_cvt_pk_bf16_f32 v10, v18, v13
	v_lshl_add_u64 v[12:13], v[16:17], 0, v[60:61]
	v_cvt_pk_bf16_f32 v11, v14, v11
	global_store_dwordx4 v[12:13], v[8:11], off
	v_max_f32_e32 v4, 0, v4
	s_nop 0
	v_mul_f32_e32 v8, v0, v0
	v_max_f32_e32 v0, 0, v5
	v_mul_f32_e32 v5, v1, v1
	v_max_f32_e32 v1, 0, v6
	v_mul_f32_e32 v6, v2, v2
	v_max_f32_e32 v2, 0, v7
	v_max_f32_e32 v3, 0, v3
	v_mul_f32_e32 v4, v4, v4
	v_mul_f32_e32 v0, v0, v0
	v_mul_f32_e32 v1, v1, v1
	v_mul_f32_e32 v2, v2, v2
	v_mul_f32_e32 v3, v3, v3
	v_cvt_pk_bf16_f32 v0, v4, v0
	v_cvt_pk_bf16_f32 v1, v1, v2
	v_cvt_pk_bf16_f32 v2, v8, v5
	v_lshl_add_u64 v[4:5], v[16:17], 0, v[52:53]
	s_and_b64 vcc, exec, s[38:39]
	s_mov_b64 s[26:27], -1
	v_cvt_pk_bf16_f32 v3, v6, v3
	global_store_dwordx4 v[4:5], v[0:3], off
	s_cbranch_vccnz .LBB0_111
	s_andn2_b64 vcc, exec, s[16:17]
	s_cbranch_vccnz .LBB0_110
	s_barrier
	s_branch .LBB0_110

; #define PG8_STAGE(bufoff, gbase, voff) do { _Pragma("unroll") for (int _i = 0; _i < 2; ++_i) \
;         __builtin_amdgcn_global_load_lds((const unsigned*)((const char*)(gbase) + (voff)[_i]), (PG8_LAS unsigned*)(lds + (bufoff) + ldsw + _i * 8192), 16, 0, 0); } while (0)
; #define PG8_WAIT_V(n) asm volatile("s_waitcnt vmcnt(" #n ")" ::: "memory")
; #define PG8_BAR __builtin_amdgcn_s_barrier()
; template <class Epi, class Sched, bool ALIGN_EPI = false, bool SP2 = false>
; __device__ __forceinline__ void gemm_phase(PG8_LAS unsigned char* lds, const Gemm g, const Sched& S, const Epi& E, const int tid_in) {
;     ...
;     if constexpr (SP2) {
;         PG8_STAGE(PG8_SB(0, 0), cB, voffB); PG8_STAGE(PG8_SB(0, 1), cB + hstepB, voffB); PG8_STAGE(PG8_SA(0, 0), cA, voffA); PG8_STAGE(PG8_SA(0, 1), cA + hstepA, voffA);
;         if (wr == 1) PG8_BAR;
;         PG8_WAIT_V(2); PG8_BAR;
;         PG8_STAGE(PG8_SB(1, 0), cB + kstepB, voffB); PG8_STAGE(PG8_SA(1, 0), cA + kstepA, voffA); PG8_STAGE(PG8_SB(1, 1), cB + hstepB + kstepB, voffB);
;         PG8_WAIT_V(6); PG8_BAR;
.LBB0_134:
	s_and_b32 s23, s22, 3
	s_lshl_b32 s21, s20, 13
	s_lshl_b32 s24, s23, 12
	s_add_u32 s4, s28, 0x4000
	v_mov_b32_e32 v157, v209
	s_addc_u32 s5, s29, 0
	s_add_i32 m0, s1, 0x18000
	v_lshl_add_u64 v[0:1], s[4:5], 0, v[156:157]
	v_mov_b32_e32 v159, v209
	global_load_lds_dwordx4 v[0:1], off
	s_add_i32 m0, s1, 0x1a000
	v_lshl_add_u64 v[0:1], s[4:5], 0, v[158:159]
	s_add_u32 s4, s26, 0x4000
	s_addc_u32 s5, s27, 0
	s_add_i32 s37, s1, 0x8000
	global_load_lds_dwordx4 v[0:1], off
	v_lshl_add_u64 v[0:1], s[4:5], 0, v[156:157]
	s_mov_b32 m0, s37
	s_add_i32 s42, s1, 0xa000
	global_load_lds_dwordx4 v[0:1], off
	v_lshl_add_u64 v[0:1], s[4:5], 0, v[158:159]
	s_add_u32 s4, s18, 0x4000
	s_mov_b32 m0, s42
	s_addc_u32 s5, s19, 0
	global_load_lds_dwordx4 v[0:1], off
	s_add_i32 m0, s1, 0x1c000
	v_lshl_add_u64 v[0:1], s[4:5], 0, v[156:157]
	global_load_lds_dwordx4 v[0:1], off
	v_lshl_add_u64 v[0:1], s[4:5], 0, v[158:159]
	s_add_i32 m0, s1, 0x1e000
	s_cmp_gt_i32 s9, 63
	global_load_lds_dwordx4 v[0:1], off
	s_waitcnt vmcnt(8)
	s_barrier
	v_bfe_u32 v0, v188, 4, 2
	v_and_b32_e32 v1, 15, v188
	v_lshlrev_b32_e32 v208, 4, v0
	v_lshlrev_b32_e32 v3, 2, v188
	s_cselect_b64 s[18:19], -1, 0
	s_add_i32 s43, s10, -2
	v_lshl_or_b32 v189, s20, 6, v1
	v_lshl_or_b32 v1, v1, 6, v208
	v_and_b32_e32 v3, 32, v3
	s_cmpk_lt_u32 s7, 0x100
	v_bitop3_b32 v4, v1, s21, v3 bitop3:0xde
	s_cselect_b64 s[20:21], -1, 0
	s_lshl_b32 s49, s6, 3
	s_lshl_b32 s4, s22, 2
	s_abs_i32 s50, s49
	v_lshlrev_b32_e32 v2, 3, v0
	v_and_or_b32 v192, s4, 4, v0
	v_cvt_f32_u32_e32 v0, s50
	s_waitcnt vmcnt(6)
	s_barrier
	s_load_dwordx2 s[4:5], s[96:97], 0xa0
	v_rcp_iflag_f32_e32 v0, v0
	v_bitop3_b32 v190, s24, v1, v3 bitop3:0xf6
	v_lshl_or_b32 v191, s23, 5, v2
	s_bfe_u32 s48, s22, 0x10001
	v_mul_f32_e32 v0, 0x4f7ffffe, v0
	v_cvt_u32_f32_e32 v0, v0
	s_waitcnt lgkmcnt(0)
	v_lshl_add_u64 v[160:161], s[4:5], 0, v[208:209]
	s_sub_i32 s4, 0, s50
	v_or_b32_e32 v193, 16, v192
	v_readfirstlane_b32 s5, v0
	s_mul_i32 s4, s4, s5
	s_mul_hi_u32 s4, s5, s4
	s_ashr_i32 s51, s53, 31
	s_ashr_i32 s52, s2, 31
	s_ashr_i32 s9, s8, 31
	s_lshl_b32 s56, s6, 4
	s_bfe_i32 s57, s6, 0x1001c
	s_mov_b32 s58, 0
	s_add_i32 s59, s5, s4
	v_lshl_add_u64 v[162:163], s[12:13], 0, v[156:157]
	v_lshl_add_u64 v[164:165], s[12:13], 0, v[158:159]
	v_add_u32_e32 v194, 0, v4
	s_branch .LBB0_137

;     __host__ __device__ bool next(int i, Unit& u) const {
;         long L = (long)i * G + c; if (L >= nwg) return false;
;         if (rev) L = nwg - 1 - L;
;         int wgid = (int)L; { const int q = nwg / NXCD, r = nwg % NXCD, xcd = wgid % NXCD, off = wgid / NXCD; wgid = (xcd < r ? xcd * (q + 1) : r * (q + 1) + (xcd - r) * q) + off; }
;         const int nig = WGM * nN, gid = wgid / nig, fm = gid * WGM, gsz = (nM - fm) < WGM ? (nM - fm) : WGM;
;         u.pm = fm + ((wgid % nig) % gsz); u.pn = (wgid % nig) / gsz; return true;
;     }
; template <class Epi, class Sched, bool ALIGN_EPI = false, bool SP2 = false>
; __device__ __forceinline__ void gemm_phase(PG8_LAS unsigned char* lds, const Gemm g, const Sched& S, const Epi& E, const int tid_in) {
;     ...
;         const bool has_next = S.next(ui + 1, nxt);
.LBB0_137:
	s_add_i32 s58, s58, 1
	s_mul_i32 s4, s58, s51
	s_mul_hi_u32 s5, s58, s53
	s_add_i32 s5, s5, s4
	s_mul_i32 s4, s58, s53
	s_add_u32 s22, s4, s2
	s_addc_u32 s23, s5, s52
	v_mov_b64_e32 v[0:1], s[8:9]
	v_cmp_ge_i64_e32 vcc, s[22:23], v[0:1]
	v_cmp_lt_i64_e64 s[40:41], s[22:23], v[0:1]
	s_cbranch_vccnz .LBB0_139
	v_readlane_b32 s4, v255, 20
	s_cmp_lg_u32 s4, 0
	s_cbranch_scc0 .Lnx_qkv_gen
	s_lshl_b32 s4, s58, 5
	s_lshr_b32 s5, s2, 3
	s_add_i32 s4, s4, s5
	s_cmp_ge_u32 s4, s49
	s_cselect_b32 s5, s49, 0
	s_cselect_b32 s6, 8, 0
	s_sub_i32 s4, s4, s5
	s_and_b32 s5, s2, 7
	s_lshl_b32 s5, s5, 4
	s_add_i32 s5, s5, s6
	s_and_b32 s6, s4, 7
	s_add_i32 s61, s5, s6
	s_lshr_b32 s60, s4, 3
	s_branch .LBB0_139
.Lnx_qkv_gen:
	s_ashr_i32 s4, s22, 31
	s_lshr_b32 s4, s4, 29
	s_add_i32 s4, s22, s4
	s_ashr_i32 s5, s4, 3
	s_and_b32 s4, s4, -8
	s_sub_i32 s4, s22, s4
	s_lshr_b32 s6, s4, 31
	s_or_b32 s6, s56, s6
	s_mul_i32 s4, s6, s4
	s_add_i32 s4, s4, s5
	s_abs_i32 s6, s4
	s_mul_hi_u32 s7, s6, s59
	s_mul_i32 s22, s7, s50
	s_ashr_i32 s5, s4, 31
	s_sub_i32 s6, s6, s22
	s_xor_b32 s5, s5, s57
	s_add_i32 s22, s7, 1
	s_sub_i32 s23, s6, s50
	s_cmp_ge_u32 s6, s50
	s_cselect_b32 s7, s22, s7
	s_cselect_b32 s6, s23, s6
	s_add_i32 s22, s7, 1
	s_cmp_ge_u32 s6, s50
	s_cselect_b32 s6, s22, s7
	s_xor_b32 s6, s6, s5
	s_sub_i32 s5, s6, s5
	s_lshl_b32 s6, s5, 3
	s_sub_i32 s7, 0x80, s6
	s_min_i32 s7, s7, 8
	s_abs_i32 s22, s7
	v_cvt_f32_u32_e32 v0, s22
	s_sub_i32 s24, 0, s22
	s_mul_i32 s5, s5, s49
	s_sub_i32 s4, s4, s5
	v_rcp_iflag_f32_e32 v0, v0
	s_abs_i32 s23, s4
	s_xor_b32 s5, s4, s7
	s_ashr_i32 s5, s5, 31
	v_mul_f32_e32 v0, 0x4f7ffffe, v0
	v_cvt_u32_f32_e32 v0, v0
	s_nop 0
	v_readfirstlane_b32 s25, v0
	s_mul_i32 s24, s24, s25
	s_mul_hi_u32 s24, s25, s24
	s_add_i32 s25, s25, s24
	s_mul_hi_u32 s24, s23, s25
	s_mul_i32 s25, s24, s22
	s_sub_i32 s23, s23, s25
	s_add_i32 s25, s24, 1
	s_sub_i32 s30, s23, s22
	s_cmp_ge_u32 s23, s22
	s_cselect_b32 s24, s25, s24
	s_cselect_b32 s23, s30, s23
	s_add_i32 s25, s24, 1
	s_cmp_ge_u32 s23, s22
	s_cselect_b32 s22, s25, s24
	s_xor_b32 s22, s22, s5
	s_sub_i32 s60, s22, s5
	s_mul_i32 s5, s60, s7
	s_sub_i32 s4, s4, s5
	s_add_i32 s61, s4, s6

; #define PG8_STAGE(bufoff, gbase, voff) do { _Pragma("unroll") for (int _i = 0; _i < 2; ++_i) \
;         __builtin_amdgcn_global_load_lds((const unsigned*)((const char*)(gbase) + (voff)[_i]), (PG8_LAS unsigned*)(lds + (bufoff) + ldsw + _i * 8192), 16, 0, 0); } while (0)
; #define PG8_WAIT_V(n) asm volatile("s_waitcnt vmcnt(" #n ")" ::: "memory")
; #define PG8_BAR __builtin_amdgcn_s_barrier()
; template <class Epi, class Sched, bool ALIGN_EPI = false, bool SP2 = false>
; __device__ __forceinline__ void gemm_phase(PG8_LAS unsigned char* lds, const Gemm g, const Sched& S, const Epi& E, const int tid_in) {
;     ...
;     if constexpr (SP2) {
;         PG8_STAGE(PG8_SB(0, 0), cB, voffB); PG8_STAGE(PG8_SB(0, 1), cB + hstepB, voffB); PG8_STAGE(PG8_SA(0, 0), cA, voffA); PG8_STAGE(PG8_SA(0, 1), cA + hstepA, voffA);
;         if (wr == 1) PG8_BAR;
;         PG8_WAIT_V(2); PG8_BAR;
;         PG8_STAGE(PG8_SB(1, 0), cB + kstepB, voffB); PG8_STAGE(PG8_SA(1, 0), cA + kstepA, voffA); PG8_STAGE(PG8_SB(1, 1), cB + hstepB + kstepB, voffB);
;         PG8_WAIT_V(6); PG8_BAR;
.LBB0_223:
	v_readlane_b32 s28, v254, 7
	v_readlane_b32 s29, v254, 8
	s_lshl_b32 s3, s36, 27
	s_mov_b64 s[4:5], s[28:29]
	s_add_u32 s3, s4, s3
	s_addc_u32 s4, s5, 0
	v_readlane_b32 s5, v255, 4
	s_bitcmp0_b32 s5, 4
	s_cselect_b32 s23, s4, 0
	s_cselect_b32 s22, s3, 0
	s_bitcmp1_b32 s5, 5
	s_cselect_b64 s[24:25], -1, 0
	s_and_b32 s87, s0, 3
	s_and_b64 s[28:29], vcc, exec
	s_movk_i32 s0, 0x4000
	s_cselect_b32 s91, s0, 0x80
	s_lshl_b32 s4, s1, 6
	s_lshl_b32 s82, s1, 13
	s_lshl_b32 s83, s87, 5
	s_lshl_b32 s5, s87, 12
	s_add_u32 s0, s48, 0x4000
	s_addc_u32 s1, s49, 0
	s_add_i32 m0, s13, 0x18000
	v_lshl_add_u64 v[0:1], s[0:1], 0, v[208:209]
	v_mov_b32_e32 v213, v209
	global_load_lds_dwordx4 v[0:1], off
	s_add_i32 m0, s13, 0x1a000
	v_lshl_add_u64 v[0:1], s[0:1], 0, v[212:213]
	s_add_u32 s0, s46, s91
	v_mov_b32_e32 v211, v209
	s_addc_u32 s1, s47, 0
	s_add_i32 s68, s13, 0x8000
	v_mov_b32_e32 v215, v209
	global_load_lds_dwordx4 v[0:1], off
	v_lshl_add_u64 v[0:1], s[0:1], 0, v[210:211]
	s_mov_b32 m0, s68
	s_add_i32 s69, s13, 0xa000
	global_load_lds_dwordx4 v[0:1], off
	v_lshl_add_u64 v[0:1], s[0:1], 0, v[214:215]
	s_add_u32 s0, s26, 0x4000
	s_mov_b32 m0, s69
	s_addc_u32 s1, s27, 0
	global_load_lds_dwordx4 v[0:1], off
	s_add_i32 m0, s13, 0x1c000
	v_lshl_add_u64 v[0:1], s[0:1], 0, v[208:209]
	global_load_lds_dwordx4 v[0:1], off
	v_lshl_add_u64 v[0:1], s[0:1], 0, v[212:213]
	s_add_i32 m0, s13, 0x1e000
	s_cmp_gt_i32 s9, 63
	global_load_lds_dwordx4 v[0:1], off
	s_waitcnt vmcnt(8)
	s_barrier
	s_cselect_b64 s[26:27], -1, 0
	s_and_b64 s[0:1], vcc, exec
	v_and_b32_e32 v0, 15, v188
	s_cselect_b32 s70, 14, 7
	s_ashr_i32 s1, s4, 3
	v_or_b32_e32 v240, s4, v0
	s_or_b32 s71, s1, 2
	s_or_b32 s0, s1, 4
	s_or_b32 s1, s1, 6
	s_ashr_i32 s72, s53, 31
	s_ashr_i32 s73, s2, 31
	s_ashr_i32 s9, s8, 31
	s_lshl_b32 s4, s6, 4
	s_lshl_b32 s75, s6, 3
	s_waitcnt lgkmcnt(0)
	s_cmp_lg_u64 s[62:63], 0
	v_readlane_b32 s30, v254, 9
	v_readlane_b32 s31, v254, 10
	s_cselect_b64 s[28:29], -1, 0
	s_cmp_lg_u64 s[22:23], 0
	s_cselect_b64 s[30:31], -1, 0
	s_cmp_lg_u64 s[58:59], 0
	v_bfe_u32 v1, v188, 4, 2
	s_cselect_b64 s[34:35], -1, 0
	s_abs_i32 s76, s75
	v_lshlrev_b32_e32 v241, 3, v1
	v_lshlrev_b32_e32 v242, 6, v0
	v_lshlrev_b32_e32 v0, 4, v1
	v_cmp_eq_u32_e64 s[38:39], 0, v1
	v_cvt_f32_u32_e32 v1, s76
	v_lshlrev_b32_e32 v3, 2, v188
	v_or_b32_e32 v2, v242, v0
	v_and_b32_e32 v243, 32, v3
	v_bitop3_b32 v3, v2, s82, v243 bitop3:0xde
	v_bitop3_b32 v244, s5, v2, v243 bitop3:0xf6
	v_rcp_iflag_f32_e32 v2, v1
	v_writelane_b32 v255, s4, 8
	s_sub_i32 s4, 0, s76
	s_waitcnt vmcnt(6)
	v_mul_f32_e32 v2, 0x4f7ffffe, v2
	v_cvt_u32_f32_e32 v2, v2
	v_mov_b32_e32 v1, v209
	s_mov_b32 s3, 0
	v_add_u32_e32 v245, 0x90, v240
	v_readfirstlane_b32 s5, v2
	s_mul_i32 s4, s4, s5
	s_mul_hi_u32 s4, s5, s4
	v_add_u32_e32 v246, 0xa0, v240
	v_add_u32_e32 v247, 0xb0, v240
	v_lshl_add_u64 v[216:217], s[62:63], 0, v[0:1]
	s_bfe_i32 s77, s6, 0x1001c
	s_add_i32 s85, s5, s4
	s_add_u32 s52, s12, -2
	v_add_u32_e32 v248, 0, v3
	s_barrier
	s_branch .LBB0_226

;     __host__ __device__ bool next(int i, Unit& u) const {
;         long L = (long)i * G + c; if (L >= nwg) return false;
;         if (rev) L = nwg - 1 - L;
;         int wgid = (int)L; { const int q = nwg / NXCD, r = nwg % NXCD, xcd = wgid % NXCD, off = wgid / NXCD; wgid = (xcd < r ? xcd * (q + 1) : r * (q + 1) + (xcd - r) * q) + off; }
;         const int nig = WGM * nN, gid = wgid / nig, fm = gid * WGM, gsz = (nM - fm) < WGM ? (nM - fm) : WGM;
;         u.pm = fm + ((wgid % nig) % gsz); u.pn = (wgid % nig) / gsz; return true;
;     }
; template <class Epi, class Sched, bool ALIGN_EPI = false, bool SP2 = false>
; __device__ __forceinline__ void gemm_phase(PG8_LAS unsigned char* lds, const Gemm g, const Sched& S, const Epi& E, const int tid_in) {
;     ...
;         const bool has_next = S.next(ui + 1, nxt);
.Lres_align_b:
.LBB0_226:
	s_add_i32 s3, s3, 1
	s_mul_i32 s4, s3, s72
	s_mul_hi_u32 s5, s3, s53
	s_add_i32 s5, s5, s4
	s_mul_i32 s4, s3, s53
	s_add_u32 s36, s4, s2
	s_addc_u32 s37, s5, s73
	s_waitcnt lgkmcnt(0)
	v_mov_b64_e32 v[0:1], s[8:9]
	v_cmp_ge_i64_e64 s[40:41], s[36:37], v[0:1]
	v_cmp_lt_i64_e64 s[42:43], s[36:37], v[0:1]
	s_and_b64 vcc, exec, s[40:41]
	s_cbranch_vccnz .LBB0_228
	v_readlane_b32 s4, v255, 20
	s_cmp_lg_u32 s4, 0
	s_cbranch_scc0 .Lnx_res_gen
	s_lshl_b32 s4, s3, 5
	s_lshr_b32 s5, s2, 3
	s_add_i32 s4, s4, s5
	v_readlane_b32 s5, v255, 8
	s_sub_i32 s4, s5, s4
	s_add_i32 s4, s4, -1
	s_cmp_ge_u32 s4, s75
	s_cselect_b32 s5, s75, 0
	s_cselect_b32 s6, 8, 0
	s_sub_i32 s4, s4, s5
	s_and_b32 s5, s2, 7
	s_lshl_b32 s5, s5, 4
	s_add_i32 s5, s5, s6
	s_and_b32 s6, s4, 7
	s_add_i32 s95, s5, s6
	s_lshr_b32 s84, s4, 3
	s_branch .LBB0_228
.Lnx_res_gen:
	s_not_b32 s4, s36
	s_add_i32 s4, s8, s4
	s_ashr_i32 s5, s4, 31
	s_lshr_b32 s5, s5, 29
	s_add_i32 s5, s4, s5
	s_ashr_i32 s6, s5, 3
	s_and_b32 s5, s5, -8
	s_sub_i32 s4, s4, s5
	v_readlane_b32 s5, v255, 20
	s_xor_b32 s4, s4, s5
	s_lshr_b32 s5, s4, 31
	v_readlane_b32 s7, v255, 8
	s_or_b32 s5, s7, s5
	s_mul_i32 s4, s5, s4
	s_add_i32 s4, s4, s6
	s_abs_i32 s6, s4
	s_mul_hi_u32 s7, s6, s85
	s_mul_i32 s36, s7, s76
	s_ashr_i32 s5, s4, 31
	s_sub_i32 s6, s6, s36
	s_xor_b32 s5, s5, s77
	s_add_i32 s36, s7, 1
	s_sub_i32 s37, s6, s76
	s_cmp_ge_u32 s6, s76
	s_cselect_b32 s7, s36, s7
	s_cselect_b32 s6, s37, s6
	s_add_i32 s36, s7, 1
	s_cmp_ge_u32 s6, s76
	s_cselect_b32 s6, s36, s7
	s_xor_b32 s6, s6, s5
	s_sub_i32 s5, s6, s5
	s_lshl_b32 s6, s5, 3
	s_sub_i32 s7, 0x80, s6
	s_min_i32 s7, s7, 8
	s_abs_i32 s36, s7
	v_cvt_f32_u32_e32 v0, s36
	s_sub_i32 s44, 0, s36
	s_mul_i32 s5, s5, s75
	s_sub_i32 s4, s4, s5
	v_rcp_iflag_f32_e32 v0, v0
	s_abs_i32 s37, s4
	s_xor_b32 s5, s4, s7
	s_ashr_i32 s5, s5, 31
	v_mul_f32_e32 v0, 0x4f7ffffe, v0
	v_cvt_u32_f32_e32 v0, v0
	s_nop 0
	v_readfirstlane_b32 s45, v0
	s_mul_i32 s44, s44, s45
	s_mul_hi_u32 s44, s45, s44
	s_add_i32 s45, s45, s44
	s_mul_hi_u32 s44, s37, s45
	s_mul_i32 s45, s44, s36
	s_sub_i32 s37, s37, s45
	s_add_i32 s45, s44, 1
	s_sub_i32 s62, s37, s36
	s_cmp_ge_u32 s37, s36
	s_cselect_b32 s44, s45, s44
	s_cselect_b32 s37, s62, s37
	s_add_i32 s45, s44, 1
	s_cmp_ge_u32 s37, s36
	s_cselect_b32 s36, s45, s44
	s_xor_b32 s36, s36, s5
	s_sub_i32 s84, s36, s5
	s_mul_i32 s5, s84, s7
	s_sub_i32 s4, s4, s5
	s_add_i32 s95, s4, s6
